# raised wave priority during GEMM K-loops (dropped at the tail) on top of flash MFMA-cluster priority
# speedup vs baseline: 1.2486x; 1.0076x over previous
; template <class Epi>
; __device__ __forceinline__ void gemm_tile(const bf16_t* __restrict__ A, const bf16_t* __restrict__ Bt, int K, int row0, int col0, const Epi& epi, char* smem,
;                                           bool prefetched, bool nvalid, int nrow0, int ncol0) {
;     ...
;     for (int kt = 0; kt < nk; ++kt) {
;         const int cur = kt & 1;
;         if (kt + 1 < nk) GLDS_STAGE(cur ^ 1, pA, pB, kt + 1);
;         const char* cb = smem + cur * 2 * TILE_B;
; #pragma unroll
;         for (int ks = 0; ks < 2; ++ks) {
;             bf16x8 a[4], b[4];
; #pragma unroll
;             for (int m = 0; m < 4; ++m) a[m] = *(const bf16x8*)(cb + offA[m][ks]);
; #pragma unroll
;             for (int n = 0; n < 4; ++n) b[n] = *(const bf16x8*)(cb + offB[n][ks]);
.LBB0_154:
	v_readfirstlane_b32 s98, v64
	v_readfirstlane_b32 s99, v65
	v_readfirstlane_b32 s10, v66
	v_readfirstlane_b32 s100, v72
	v_readfirstlane_b32 s101, v73
	v_readfirstlane_b32 s13, v149
	s_nop 3
	s_sub_u32 s14, s10, s98
	s_and_b32 s98, s98, 0xffffff80
	s_and_b32 s100, s100, 0xffffff80
	s_nop 1
	v_subrev_u32_e32 v254, s98, v64
	v_subrev_u32_e32 v255, s100, v72
	s_add_i32 s12, s13, 0x8000
	s_mov_b32 m0, s12
	s_nop 0
	global_load_lds_dwordx4 v254, s[98:99]
	s_add_i32 m0, s12, 0x1000
	s_add_u32 s10, s98, s14
	s_addc_u32 s11, s99, 0
	global_load_lds_dwordx4 v254, s[10:11]
	s_add_i32 m0, s12, 0x2000
	s_add_u32 s10, s10, s14
	s_addc_u32 s11, s11, 0
	global_load_lds_dwordx4 v254, s[10:11]
	s_add_i32 m0, s12, 0x3000
	s_add_u32 s10, s10, s14
	s_addc_u32 s11, s11, 0
	global_load_lds_dwordx4 v254, s[10:11]
	s_add_u32 s98, s98, 0x80
	s_addc_u32 s99, s99, 0
	ds_read_b128 v[182:185], v139
	ds_read_b128 v[64:67], v142 offset:16384
	ds_read_b128 v[68:71], v142 offset:16896
	ds_read_b128 v[72:75], v142 offset:20480
	ds_read_b128 v[76:79], v142 offset:20992
	ds_read_b128 v[186:189], v139 offset:2048
	ds_read_b128 v[246:249], v139 offset:4096
	ds_read_b128 v[250:253], v139 offset:6144
	s_setprio 1

; __device__ __forceinline__ f32x4 mfma16(bf16x8 a, bf16x8 b, f32x4 c) { return __builtin_amdgcn_mfma_f32_16x16x32_bf16(a, b, c, 0, 0, 0); }
; template <class Epi>
; __device__ __forceinline__ void gemm_tile(const bf16_t* __restrict__ A, const bf16_t* __restrict__ Bt, int K, int row0, int col0, const Epi& epi, char* smem,
;                                           bool prefetched, bool nvalid, int nrow0, int ncol0) {
;     ...
; #pragma unroll
;         for (int ks = 0; ks < 2; ++ks) {
;             bf16x8 a[4], b[4];
; #pragma unroll
;             for (int m = 0; m < 4; ++m) a[m] = *(const bf16x8*)(cb + offA[m][ks]);
; #pragma unroll
;             for (int n = 0; n < 4; ++n) b[n] = *(const bf16x8*)(cb + offB[n][ks]);
; #pragma unroll
;             for (int m = 0; m < 4; ++m)
; #pragma unroll
;                 for (int n = 0; n < 4; ++n) acc[m][n] = mfma16(b[n], a[m], acc[m][n]);
;         }
;         asm volatile("s_waitcnt vmcnt(0)" ::: "memory");
;         __syncthreads();
;     }
;     if (nvalid) { const bf16_t* qA = A + (size_t)nrow0 * K; const bf16_t* qB = Bt + (size_t)ncol0 * K; GLDS_STAGE(0, qA, qB, 0); }
; template <class Epi>
; __device__ __forceinline__ void gemm_phase(const bf16_t* A, const bf16_t* Bt, int M, int N, int K, const Epi& epi, char* smem) {
;     ...
;     for (int i = blockIdx.x; i < ntiles; i += G) {
;         const int j = i + G; const bool nv = j < ntiles;
;         gemm_tile(A, Bt, K, (i / nN) << 7, (i % nN) << 7, epi, smem, pre, nv, (j / nN) << 7, (j % nN) << 7);
.Lgk_tail_154:
	s_setprio 0
	v_mfma_f32_16x16x32_bf16 v[32:35], v[80:83], v[246:249], v[32:35]
	v_mfma_f32_16x16x32_bf16 v[36:39], v[128:131], v[246:249], v[36:39]
	v_mfma_f32_16x16x32_bf16 v[40:43], v[174:177], v[246:249], v[40:43]
	v_mfma_f32_16x16x32_bf16 v[44:47], v[178:181], v[246:249], v[44:47]
	v_mfma_f32_16x16x32_bf16 v[48:51], v[80:83], v[250:253], v[48:51]
	v_mfma_f32_16x16x32_bf16 v[52:55], v[128:131], v[250:253], v[52:55]
	v_mfma_f32_16x16x32_bf16 v[56:59], v[174:177], v[250:253], v[56:59]
	v_mfma_f32_16x16x32_bf16 v[60:63], v[178:181], v[250:253], v[60:63]
	ds_read_b128 v[64:67], v142 offset:49152
	ds_read_b128 v[68:71], v139 offset:32768
	ds_read_b128 v[72:75], v142 offset:49664
	ds_read_b128 v[76:79], v142 offset:53248
	ds_read_b128 v[80:83], v142 offset:53760
	s_add_i32 s21, s21, s58
	s_waitcnt lgkmcnt(3)
	v_mfma_f32_16x16x32_bf16 v[0:3], v[64:67], v[68:71], v[0:3]
	s_cmpk_gt_i32 s21, 0x10ff
	s_cselect_b64 s[8:9], -1, 0
	s_cmpk_lt_i32 s21, 0x1100
	s_waitcnt lgkmcnt(2)
	v_mfma_f32_16x16x32_bf16 v[4:7], v[72:75], v[68:71], v[4:7]
	ds_read_b128 v[182:185], v141 offset:49152
	ds_read_b128 v[186:189], v141 offset:53760
	s_waitcnt lgkmcnt(3)
	v_mfma_f32_16x16x32_bf16 v[8:11], v[76:79], v[68:71], v[8:11]
	s_waitcnt lgkmcnt(2)
	v_mfma_f32_16x16x32_bf16 v[12:15], v[80:83], v[68:71], v[12:15]
	ds_read_b128 v[68:71], v139 offset:34816
	s_waitcnt lgkmcnt(0)
	v_mfma_f32_16x16x32_bf16 v[16:19], v[64:67], v[68:71], v[16:19]
	v_mfma_f32_16x16x32_bf16 v[20:23], v[72:75], v[68:71], v[20:23]
	v_mfma_f32_16x16x32_bf16 v[24:27], v[76:79], v[68:71], v[24:27]
	v_mfma_f32_16x16x32_bf16 v[28:31], v[80:83], v[68:71], v[28:31]
	ds_read_b128 v[68:71], v139 offset:36864
	s_waitcnt lgkmcnt(0)
	v_mfma_f32_16x16x32_bf16 v[128:131], v[64:67], v[68:71], v[32:35]
	s_nop 2
	ds_read_b128 v[32:35], v139 offset:38912
	v_mfma_f32_16x16x32_bf16 v[174:177], v[72:75], v[68:71], v[36:39]
	v_mfma_f32_16x16x32_bf16 v[178:181], v[76:79], v[68:71], v[40:43]
	v_mfma_f32_16x16x32_bf16 v[68:71], v[80:83], v[68:71], v[44:47]
	s_waitcnt lgkmcnt(0)
	v_mfma_f32_16x16x32_bf16 v[64:67], v[64:67], v[32:35], v[48:51]
	v_mfma_f32_16x16x32_bf16 v[72:75], v[72:75], v[32:35], v[52:55]
	v_mfma_f32_16x16x32_bf16 v[76:79], v[76:79], v[32:35], v[56:59]
	v_mfma_f32_16x16x32_bf16 v[80:83], v[80:83], v[32:35], v[60:63]
	ds_read_b128 v[32:35], v140 offset:32768
	s_waitcnt lgkmcnt(0)
	v_mfma_f32_16x16x32_bf16 v[56:59], v[182:185], v[32:35], v[0:3]
	s_nop 2
	ds_read_b128 v[0:3], v141 offset:49664
	s_waitcnt lgkmcnt(0)
	v_mfma_f32_16x16x32_bf16 v[60:63], v[0:3], v[32:35], v[4:7]
	s_nop 2
	ds_read_b128 v[4:7], v141 offset:53248
	s_waitcnt lgkmcnt(0)
	v_mfma_f32_16x16x32_bf16 v[48:51], v[4:7], v[32:35], v[8:11]
	s_nop 2
	ds_read_b128 v[8:11], v140 offset:34816
	v_mfma_f32_16x16x32_bf16 v[52:55], v[186:189], v[32:35], v[12:15]
	s_waitcnt lgkmcnt(0)
	v_mfma_f32_16x16x32_bf16 v[40:43], v[182:185], v[8:11], v[16:19]
	v_mfma_f32_16x16x32_bf16 v[44:47], v[0:3], v[8:11], v[20:23]
	v_mfma_f32_16x16x32_bf16 v[32:35], v[4:7], v[8:11], v[24:27]
	v_mfma_f32_16x16x32_bf16 v[36:39], v[186:189], v[8:11], v[28:31]
	ds_read_b128 v[8:11], v140 offset:36864
	s_waitcnt lgkmcnt(0)
	v_mfma_f32_16x16x32_bf16 v[20:23], v[186:189], v[8:11], v[68:71]
	s_nop 2
	ds_read_b128 v[68:71], v140 offset:38912
	s_waitcnt vmcnt(0)
	v_mfma_f32_16x16x32_bf16 v[24:27], v[182:185], v[8:11], v[128:131]
	s_waitcnt lgkmcnt(0)
	s_barrier
	v_mfma_f32_16x16x32_bf16 v[28:31], v[0:3], v[8:11], v[174:177]
	v_mfma_f32_16x16x32_bf16 v[16:19], v[4:7], v[8:11], v[178:181]
	v_mfma_f32_16x16x32_bf16 v[8:11], v[182:185], v[68:71], v[64:67]
	v_mfma_f32_16x16x32_bf16 v[12:15], v[0:3], v[68:71], v[72:75]
	v_mfma_f32_16x16x32_bf16 v[0:3], v[4:7], v[68:71], v[76:79]
	v_mfma_f32_16x16x32_bf16 v[4:7], v[186:189], v[68:71], v[80:83]
	s_cbranch_scc0 .LBB0_157
	s_mul_hi_i32 s0, s21, 0x78787879
	s_lshr_b32 s1, s0, 31
	s_ashr_i32 s0, s0, 3
	s_add_i32 s1, s0, s1
	s_lshl_b32 s0, s1, 7
	s_mul_i32 s1, s1, 17
	s_sub_i32 s1, s21, s1
	s_lshl_b32 s10, s1, 7
	s_ashr_i32 s1, s0, 31
	s_lshl_b64 s[0:1], s[0:1], 11
	v_readlane_b32 s5, v245, 53
	s_add_u32 s0, s5, s0
	v_readlane_b32 s5, v245, 54
	s_addc_u32 s1, s5, s1
	s_ashr_i32 s11, s10, 31
	s_lshl_b64 s[10:11], s[10:11], 11
	s_add_u32 s10, s56, s10
	v_readfirstlane_b32 s5, v149
	s_addc_u32 s11, s57, s11
	s_mov_b32 m0, s5
	v_readfirstlane_b32 s5, v159
	global_load_lds_dwordx4 v167, s[0:1]
	v_lshl_add_u64 v[64:65], v[84:85], 1, s[10:11]
	s_mov_b32 m0, s5
	v_readfirstlane_b32 s5, v160
	global_load_lds_dwordx4 v[64:65], off
	s_mov_b32 m0, s5
	v_readfirstlane_b32 s5, v161
	global_load_lds_dwordx4 v168, s[0:1]
	v_lshl_add_u64 v[64:65], v[86:87], 1, s[10:11]
	s_mov_b32 m0, s5
	v_readfirstlane_b32 s5, v162
	global_load_lds_dwordx4 v[64:65], off
	s_mov_b32 m0, s5
	v_readfirstlane_b32 s5, v163
	global_load_lds_dwordx4 v169, s[0:1]
	v_lshl_add_u64 v[64:65], v[88:89], 1, s[10:11]
	s_mov_b32 m0, s5
	v_readfirstlane_b32 s5, v164
	global_load_lds_dwordx4 v[64:65], off
	s_mov_b32 m0, s5
	v_lshl_add_u64 v[64:65], v[90:91], 1, s[10:11]
	global_load_lds_dwordx4 v170, s[0:1]
	v_readfirstlane_b32 s0, v165
	s_mov_b32 m0, s0
	s_nop 0
	global_load_lds_dwordx4 v[64:65], off

; template <class Epi>
; __device__ __forceinline__ void gemm_tile(const bf16_t* __restrict__ A, const bf16_t* __restrict__ Bt, int K, int row0, int col0, const Epi& epi, char* smem,
;                                           bool prefetched, bool nvalid, int nrow0, int ncol0) {
;     ...
;     for (int kt = 0; kt < nk; ++kt) {
;         const int cur = kt & 1;
;         if (kt + 1 < nk) GLDS_STAGE(cur ^ 1, pA, pB, kt + 1);
;         const char* cb = smem + cur * 2 * TILE_B;
; #pragma unroll
;         for (int ks = 0; ks < 2; ++ks) {
;             bf16x8 a[4], b[4];
; #pragma unroll
;             for (int m = 0; m < 4; ++m) a[m] = *(const bf16x8*)(cb + offA[m][ks]);
; #pragma unroll
;             for (int n = 0; n < 4; ++n) b[n] = *(const bf16x8*)(cb + offB[n][ks]);
.LBB0_197:
	v_readfirstlane_b32 s98, v106
	v_readfirstlane_b32 s99, v107
	v_readfirstlane_b32 s8, v108
	v_readfirstlane_b32 s100, v120
	v_readfirstlane_b32 s101, v121
	v_readfirstlane_b32 s11, v149
	s_nop 3
	s_sub_u32 s15, s8, s98
	s_and_b32 s98, s98, 0xffffff80
	s_and_b32 s100, s100, 0xffffff80
	s_nop 1
	v_subrev_u32_e32 v254, s98, v106
	v_subrev_u32_e32 v255, s100, v120
	s_add_i32 s10, s11, 0x8000
	s_mov_b32 m0, s10
	s_nop 0
	global_load_lds_dwordx4 v254, s[98:99]
	s_add_i32 m0, s10, 0x1000
	s_add_u32 s8, s98, s15
	s_addc_u32 s9, s99, 0
	global_load_lds_dwordx4 v254, s[8:9]
	s_add_i32 m0, s10, 0x2000
	s_add_u32 s8, s8, s15
	s_addc_u32 s9, s9, 0
	global_load_lds_dwordx4 v254, s[8:9]
	s_add_i32 m0, s10, 0x3000
	s_add_u32 s8, s8, s15
	s_addc_u32 s9, s9, 0
	global_load_lds_dwordx4 v254, s[8:9]
	s_add_u32 s98, s98, 0x80
	s_addc_u32 s99, s99, 0
	ds_read_b128 v[188:191], v117
	ds_read_b128 v[106:109], v130 offset:16384
	ds_read_b128 v[118:121], v130 offset:16896
	ds_read_b128 v[122:125], v130 offset:20480
	ds_read_b128 v[168:171], v130 offset:20992
	ds_read_b128 v[192:195], v117 offset:2048
	ds_read_b128 v[196:199], v117 offset:4096
	ds_read_b128 v[246:249], v117 offset:6144
	s_setprio 1

; __device__ __forceinline__ f32x4 mfma16(bf16x8 a, bf16x8 b, f32x4 c) { return __builtin_amdgcn_mfma_f32_16x16x32_bf16(a, b, c, 0, 0, 0); }
; template <class Epi>
; __device__ __forceinline__ void gemm_tile(const bf16_t* __restrict__ A, const bf16_t* __restrict__ Bt, int K, int row0, int col0, const Epi& epi, char* smem,
;                                           bool prefetched, bool nvalid, int nrow0, int ncol0) {
;     ...
; #pragma unroll
;         for (int ks = 0; ks < 2; ++ks) {
;             bf16x8 a[4], b[4];
; #pragma unroll
;             for (int m = 0; m < 4; ++m) a[m] = *(const bf16x8*)(cb + offA[m][ks]);
; #pragma unroll
;             for (int n = 0; n < 4; ++n) b[n] = *(const bf16x8*)(cb + offB[n][ks]);
; #pragma unroll
;             for (int m = 0; m < 4; ++m)
; #pragma unroll
;                 for (int n = 0; n < 4; ++n) acc[m][n] = mfma16(b[n], a[m], acc[m][n]);
;         }
;         asm volatile("s_waitcnt vmcnt(0)" ::: "memory");
;         __syncthreads();
;     }
;     if (nvalid) { const bf16_t* qA = A + (size_t)nrow0 * K; const bf16_t* qB = Bt + (size_t)ncol0 * K; GLDS_STAGE(0, qA, qB, 0); }
; template <class E1, class E2>
; __device__ __forceinline__ void gemm_phase2(const bf16_t* A1, const bf16_t* B1, int M1, int N1, const E1& e1,
;                                             const bf16_t* A2, const bf16_t* B2, int M2, int N2, const E2& e2, int K, char* smem) {
;     ...
;     for (int i = (blockIdx.x + (G >> 1)) % G; i < nt2; i += G) {
;         const int j = i + G; const bool nv = j < nt2;
;         gemm_tile(A2, B2, K, (i % nM2) << 7, (i / nM2) << 7, e2, smem, pre, nv, (j % nM2) << 7, (j / nM2) << 7);
.Lgk_tail_197:
	s_setprio 0
	v_mfma_f32_16x16x32_bf16 v[32:35], v[172:175], v[196:199], v[32:35]
	v_mfma_f32_16x16x32_bf16 v[36:39], v[176:179], v[196:199], v[36:39]
	v_mfma_f32_16x16x32_bf16 v[40:43], v[180:183], v[196:199], v[40:43]
	v_mfma_f32_16x16x32_bf16 v[44:47], v[184:187], v[196:199], v[44:47]
	v_mfma_f32_16x16x32_bf16 v[48:51], v[172:175], v[246:249], v[48:51]
	v_mfma_f32_16x16x32_bf16 v[52:55], v[176:179], v[246:249], v[52:55]
	v_mfma_f32_16x16x32_bf16 v[56:59], v[180:183], v[246:249], v[56:59]
	v_mfma_f32_16x16x32_bf16 v[60:63], v[184:187], v[246:249], v[60:63]
	ds_read_b128 v[106:109], v130 offset:49152
	ds_read_b128 v[118:121], v117 offset:32768
	ds_read_b128 v[122:125], v130 offset:49664
	ds_read_b128 v[168:171], v130 offset:53248
	ds_read_b128 v[172:175], v130 offset:53760
	s_add_i32 s14, s14, s58
	s_waitcnt lgkmcnt(3)
	v_mfma_f32_16x16x32_bf16 v[0:3], v[106:109], v[118:121], v[0:3]
	s_cmpk_gt_i32 s14, 0x3ff
	s_cselect_b64 s[4:5], -1, 0
	s_cmpk_lt_i32 s14, 0x400
	s_waitcnt lgkmcnt(2)
	v_mfma_f32_16x16x32_bf16 v[4:7], v[122:125], v[118:121], v[4:7]
	ds_read_b128 v[188:191], v129 offset:49152
	ds_read_b128 v[192:195], v129 offset:53248
	ds_read_b128 v[196:199], v129 offset:53760
	s_waitcnt lgkmcnt(4)
	v_mfma_f32_16x16x32_bf16 v[8:11], v[168:171], v[118:121], v[8:11]
	s_waitcnt lgkmcnt(3)
	v_mfma_f32_16x16x32_bf16 v[12:15], v[172:175], v[118:121], v[12:15]
	ds_read_b128 v[118:121], v117 offset:34816
	s_waitcnt lgkmcnt(0)
	v_mfma_f32_16x16x32_bf16 v[16:19], v[106:109], v[118:121], v[16:19]
	v_mfma_f32_16x16x32_bf16 v[20:23], v[122:125], v[118:121], v[20:23]
	v_mfma_f32_16x16x32_bf16 v[24:27], v[168:171], v[118:121], v[24:27]
	v_mfma_f32_16x16x32_bf16 v[28:31], v[172:175], v[118:121], v[28:31]
	ds_read_b128 v[118:121], v117 offset:36864
	s_waitcnt lgkmcnt(0)
	v_mfma_f32_16x16x32_bf16 v[176:179], v[106:109], v[118:121], v[32:35]
	s_nop 2
	ds_read_b128 v[32:35], v117 offset:38912
	v_mfma_f32_16x16x32_bf16 v[180:183], v[122:125], v[118:121], v[36:39]
	v_mfma_f32_16x16x32_bf16 v[184:187], v[168:171], v[118:121], v[40:43]
	v_mfma_f32_16x16x32_bf16 v[118:121], v[172:175], v[118:121], v[44:47]
	s_waitcnt lgkmcnt(0)
	v_mfma_f32_16x16x32_bf16 v[106:109], v[106:109], v[32:35], v[48:51]
	v_mfma_f32_16x16x32_bf16 v[122:125], v[122:125], v[32:35], v[52:55]
	v_mfma_f32_16x16x32_bf16 v[168:171], v[168:171], v[32:35], v[56:59]
	v_mfma_f32_16x16x32_bf16 v[172:175], v[172:175], v[32:35], v[60:63]
	ds_read_b128 v[32:35], v128 offset:32768
	s_waitcnt lgkmcnt(0)
	v_mfma_f32_16x16x32_bf16 v[56:59], v[188:191], v[32:35], v[0:3]
	s_nop 2
	ds_read_b128 v[0:3], v129 offset:49664
	s_waitcnt lgkmcnt(0)
	v_mfma_f32_16x16x32_bf16 v[60:63], v[0:3], v[32:35], v[4:7]
	s_nop 2
	ds_read_b128 v[4:7], v128 offset:34816
	v_mfma_f32_16x16x32_bf16 v[48:51], v[192:195], v[32:35], v[8:11]
	v_mfma_f32_16x16x32_bf16 v[52:55], v[196:199], v[32:35], v[12:15]
	s_nop 2
	ds_read_b128 v[12:15], v128 offset:38912
	s_waitcnt lgkmcnt(1)
	v_mfma_f32_16x16x32_bf16 v[44:47], v[188:191], v[4:7], v[16:19]
	v_mfma_f32_16x16x32_bf16 v[40:43], v[0:3], v[4:7], v[20:23]
	v_mfma_f32_16x16x32_bf16 v[36:39], v[192:195], v[4:7], v[24:27]
	v_mfma_f32_16x16x32_bf16 v[32:35], v[196:199], v[4:7], v[28:31]
	ds_read_b128 v[4:7], v128 offset:36864
	s_waitcnt vmcnt(0)
	s_waitcnt lgkmcnt(0)
	v_mfma_f32_16x16x32_bf16 v[28:31], v[188:191], v[4:7], v[176:179]
	s_barrier
	v_mfma_f32_16x16x32_bf16 v[24:27], v[0:3], v[4:7], v[180:183]
	v_mfma_f32_16x16x32_bf16 v[20:23], v[192:195], v[4:7], v[184:187]
	v_mfma_f32_16x16x32_bf16 v[16:19], v[196:199], v[4:7], v[118:121]
	v_mfma_f32_16x16x32_bf16 v[4:7], v[188:191], v[12:15], v[106:109]
	v_mfma_f32_16x16x32_bf16 v[8:11], v[0:3], v[12:15], v[122:125]
	v_mfma_f32_16x16x32_bf16 v[0:3], v[192:195], v[12:15], v[168:171]
	v_mfma_f32_16x16x32_bf16 v[12:15], v[196:199], v[12:15], v[172:175]
	s_cbranch_scc0 .LBB0_191
	s_and_b32 s8, s14, 7
	s_lshl_b32 s8, s8, 2
	s_bfe_u32 s9, s14, 0x20003
	s_or_b32 s8, s8, s9
	s_and_b32 s9, s14, 0xffffffe0
	s_or_b32 s9, s8, s9
	s_ashr_i32 s1, s9, 31
	s_lshr_b32 s1, s1, 30
	s_add_i32 s1, s9, s1
	s_and_b32 s6, s1, 0x1fffffc
	s_sub_i32 s6, s9, s6
	s_lshl_b32 s6, s6, 7
	s_lshl_b32 s1, s1, 5
	s_ashr_i32 s7, s6, 31
	s_and_b32 s8, s1, 0xffffff80
	s_lshl_b64 s[6:7], s[6:7], 11
	s_add_u32 s6, s12, s6
	s_addc_u32 s7, s13, s7
	s_ashr_i32 s9, s8, 31
	s_lshl_b64 s[8:9], s[8:9], 11
	v_readlane_b32 s1, v245, 53
	s_add_u32 s8, s1, s8
	v_readlane_b32 s1, v245, 54
	s_addc_u32 s9, s1, s9
	v_readfirstlane_b32 s1, v149
	s_mov_b32 m0, s1
	v_readfirstlane_b32 s1, v131
	global_load_lds_dwordx4 v163, s[6:7]
	v_lshl_add_u64 v[106:107], v[64:65], 1, s[8:9]
	s_mov_b32 m0, s1
	v_readfirstlane_b32 s1, v139
	global_load_lds_dwordx4 v[106:107], off
	s_mov_b32 m0, s1
	v_readfirstlane_b32 s1, v140
	global_load_lds_dwordx4 v164, s[6:7]
	v_lshl_add_u64 v[106:107], v[66:67], 1, s[8:9]
	s_mov_b32 m0, s1
	v_readfirstlane_b32 s1, v141
	global_load_lds_dwordx4 v[106:107], off
	s_mov_b32 m0, s1
	v_readfirstlane_b32 s1, v142
	global_load_lds_dwordx4 v165, s[6:7]
	v_lshl_add_u64 v[106:107], v[68:69], 1, s[8:9]
	s_mov_b32 m0, s1
	v_readfirstlane_b32 s1, v143
	global_load_lds_dwordx4 v[106:107], off
	s_mov_b32 m0, s1
	v_readfirstlane_b32 s1, v144
	global_load_lds_dwordx4 v166, s[6:7]
	v_lshl_add_u64 v[106:107], v[70:71], 1, s[8:9]
	s_mov_b32 m0, s1
	s_nop 0
	global_load_lds_dwordx4 v[106:107], off
	s_branch .LBB0_191

; template <class Epi>
; __device__ __forceinline__ void gemm_tile(const bf16_t* __restrict__ A, const bf16_t* __restrict__ Bt, int K, int row0, int col0, const Epi& epi, char* smem,
;                                           bool prefetched, bool nvalid, int nrow0, int ncol0) {
;     ...
;     for (int kt = 0; kt < nk; ++kt) {
;         const int cur = kt & 1;
;         if (kt + 1 < nk) GLDS_STAGE(cur ^ 1, pA, pB, kt + 1);
;         const char* cb = smem + cur * 2 * TILE_B;
; #pragma unroll
;         for (int ks = 0; ks < 2; ++ks) {
;             bf16x8 a[4], b[4];
; #pragma unroll
;             for (int m = 0; m < 4; ++m) a[m] = *(const bf16x8*)(cb + offA[m][ks]);
; #pragma unroll
;             for (int n = 0; n < 4; ++n) b[n] = *(const bf16x8*)(cb + offB[n][ks]);
.LBB0_460:
	v_readfirstlane_b32 s98, v94
	v_readfirstlane_b32 s99, v95
	v_readfirstlane_b32 s8, v96
	v_readfirstlane_b32 s100, v102
	v_readfirstlane_b32 s101, v103
	v_readfirstlane_b32 s12, v149
	s_nop 3
	s_sub_u32 s13, s8, s98
	s_and_b32 s98, s98, 0xffffff80
	s_and_b32 s100, s100, 0xffffff80
	s_nop 1
	v_subrev_u32_e32 v254, s98, v94
	v_subrev_u32_e32 v255, s100, v102
	s_add_i32 s11, s12, 0x8000
	s_mov_b32 m0, s11
	s_nop 0
	global_load_lds_dwordx4 v254, s[98:99]
	s_add_i32 m0, s11, 0x1000
	s_add_u32 s8, s98, s13
	s_addc_u32 s9, s99, 0
	global_load_lds_dwordx4 v254, s[8:9]
	s_add_i32 m0, s11, 0x2000
	s_add_u32 s8, s8, s13
	s_addc_u32 s9, s9, 0
	global_load_lds_dwordx4 v254, s[8:9]
	s_add_i32 m0, s11, 0x3000
	s_add_u32 s8, s8, s13
	s_addc_u32 s9, s9, 0
	global_load_lds_dwordx4 v254, s[8:9]
	s_add_u32 s98, s98, 0x80
	s_addc_u32 s99, s99, 0
	ds_read_b128 v[174:177], v110
	ds_read_b128 v[94:97], v87 offset:16384
	ds_read_b128 v[98:101], v87 offset:16896
	ds_read_b128 v[102:105], v87 offset:20480
	ds_read_b128 v[106:109], v87 offset:20992
	ds_read_b128 v[178:181], v110 offset:2048
	ds_read_b128 v[246:249], v110 offset:4096
	ds_read_b128 v[250:253], v110 offset:6144
	s_setprio 1

; __device__ __forceinline__ f32x4 mfma16(bf16x8 a, bf16x8 b, f32x4 c) { return __builtin_amdgcn_mfma_f32_16x16x32_bf16(a, b, c, 0, 0, 0); }
; template <class Epi>
; __device__ __forceinline__ void gemm_tile(const bf16_t* __restrict__ A, const bf16_t* __restrict__ Bt, int K, int row0, int col0, const Epi& epi, char* smem,
;                                           bool prefetched, bool nvalid, int nrow0, int ncol0) {
;     ...
;     for (int kt = 0; kt < nk; ++kt) {
;         const int cur = kt & 1;
;         if (kt + 1 < nk) GLDS_STAGE(cur ^ 1, pA, pB, kt + 1);
;         const char* cb = smem + cur * 2 * TILE_B;
; #pragma unroll
;         for (int ks = 0; ks < 2; ++ks) {
;             bf16x8 a[4], b[4];
; #pragma unroll
;             for (int m = 0; m < 4; ++m) a[m] = *(const bf16x8*)(cb + offA[m][ks]);
; #pragma unroll
;             for (int n = 0; n < 4; ++n) b[n] = *(const bf16x8*)(cb + offB[n][ks]);
; #pragma unroll
;             for (int m = 0; m < 4; ++m)
; #pragma unroll
;                 for (int n = 0; n < 4; ++n) acc[m][n] = mfma16(b[n], a[m], acc[m][n]);
;         }
;         asm volatile("s_waitcnt vmcnt(0)" ::: "memory");
;         __syncthreads();
;     }
;     if (nvalid) { const bf16_t* qA = A + (size_t)nrow0 * K; const bf16_t* qB = Bt + (size_t)ncol0 * K; GLDS_STAGE(0, qA, qB, 0); }
; template <class Epi>
; __device__ __forceinline__ void gemm_phase(const bf16_t* A, const bf16_t* Bt, int M, int N, int K, const Epi& epi, char* smem) {
;     ...
;     for (int i = blockIdx.x; i < ntiles; i += G) {
;         const int j = i + G; const bool nv = j < ntiles;
;         gemm_tile(A, Bt, K, (i / nN) << 7, (i % nN) << 7, epi, smem, pre, nv, (j / nN) << 7, (j % nN) << 7);
;         pre = nv;
.Lgk_tail_460:
	s_setprio 0
	v_mfma_f32_16x16x32_bf16 v[32:35], v[142:145], v[246:249], v[32:35]
	v_mfma_f32_16x16x32_bf16 v[36:39], v[162:165], v[246:249], v[36:39]
	v_mfma_f32_16x16x32_bf16 v[40:43], v[166:169], v[246:249], v[40:43]
	v_mfma_f32_16x16x32_bf16 v[44:47], v[170:173], v[246:249], v[44:47]
	v_mfma_f32_16x16x32_bf16 v[48:51], v[142:145], v[250:253], v[48:51]
	v_mfma_f32_16x16x32_bf16 v[52:55], v[162:165], v[250:253], v[52:55]
	v_mfma_f32_16x16x32_bf16 v[56:59], v[166:169], v[250:253], v[56:59]
	v_mfma_f32_16x16x32_bf16 v[60:63], v[170:173], v[250:253], v[60:63]
	ds_read_b128 v[94:97], v87 offset:49152
	ds_read_b128 v[98:101], v87 offset:49664
	ds_read_b128 v[102:105], v110 offset:32768
	ds_read_b128 v[106:109], v110 offset:34816
	ds_read_b128 v[142:145], v87 offset:53248
	ds_read_b128 v[162:165], v87 offset:53760
	s_add_i32 s16, s16, s58
	s_waitcnt lgkmcnt(3)
	v_mfma_f32_16x16x32_bf16 v[0:3], v[94:97], v[102:105], v[0:3]
	s_cmpk_gt_i32 s16, 0x7ff
	s_cselect_b64 s[6:7], -1, 0
	s_cmpk_lt_i32 s16, 0x800
	v_mfma_f32_16x16x32_bf16 v[4:7], v[98:101], v[102:105], v[4:7]
	s_waitcnt lgkmcnt(1)
	v_mfma_f32_16x16x32_bf16 v[8:11], v[142:145], v[102:105], v[8:11]
	s_waitcnt lgkmcnt(0)
	v_mfma_f32_16x16x32_bf16 v[12:15], v[162:165], v[102:105], v[12:15]
	v_mfma_f32_16x16x32_bf16 v[16:19], v[94:97], v[106:109], v[16:19]
	v_mfma_f32_16x16x32_bf16 v[20:23], v[98:101], v[106:109], v[20:23]
	v_mfma_f32_16x16x32_bf16 v[24:27], v[142:145], v[106:109], v[24:27]
	v_mfma_f32_16x16x32_bf16 v[28:31], v[162:165], v[106:109], v[28:31]
	ds_read_b128 v[102:105], v110 offset:36864
	ds_read_b128 v[106:109], v110 offset:38912
	ds_read_b128 v[178:181], v118 offset:49152
	s_waitcnt lgkmcnt(2)
	v_mfma_f32_16x16x32_bf16 v[166:169], v[94:97], v[102:105], v[32:35]
	v_mfma_f32_16x16x32_bf16 v[170:173], v[98:101], v[102:105], v[36:39]
	v_mfma_f32_16x16x32_bf16 v[174:177], v[142:145], v[102:105], v[40:43]
	v_mfma_f32_16x16x32_bf16 v[102:105], v[162:165], v[102:105], v[44:47]
	s_waitcnt lgkmcnt(1)
	v_mfma_f32_16x16x32_bf16 v[94:97], v[94:97], v[106:109], v[48:51]
	v_mfma_f32_16x16x32_bf16 v[98:101], v[98:101], v[106:109], v[52:55]
	v_mfma_f32_16x16x32_bf16 v[142:145], v[142:145], v[106:109], v[56:59]
	v_mfma_f32_16x16x32_bf16 v[106:109], v[162:165], v[106:109], v[60:63]
	ds_read_b128 v[162:165], v118 offset:49664
	ds_read_b128 v[32:35], v111 offset:32768
	ds_read_b128 v[36:39], v111 offset:34816
	ds_read_b128 v[182:185], v118 offset:53760
	s_waitcnt lgkmcnt(2)
	v_mfma_f32_16x16x32_bf16 v[52:55], v[178:181], v[32:35], v[0:3]
	s_nop 2
	ds_read_b128 v[0:3], v118 offset:53248
	v_mfma_f32_16x16x32_bf16 v[56:59], v[162:165], v[32:35], v[4:7]
	s_nop 2
	ds_read_b128 v[4:7], v111 offset:36864
	ds_read_b128 v[186:189], v111 offset:38912
	s_waitcnt vmcnt(0)
	s_waitcnt lgkmcnt(0)
	v_mfma_f32_16x16x32_bf16 v[60:63], v[0:3], v[32:35], v[8:11]
	s_barrier
	v_mfma_f32_16x16x32_bf16 v[48:51], v[182:185], v[32:35], v[12:15]
	v_mfma_f32_16x16x32_bf16 v[44:47], v[178:181], v[36:39], v[16:19]
	v_mfma_f32_16x16x32_bf16 v[40:43], v[162:165], v[36:39], v[20:23]
	v_mfma_f32_16x16x32_bf16 v[32:35], v[0:3], v[36:39], v[24:27]
	v_mfma_f32_16x16x32_bf16 v[24:27], v[182:185], v[36:39], v[28:31]
	v_mfma_f32_16x16x32_bf16 v[36:39], v[178:181], v[4:7], v[166:169]
	v_mfma_f32_16x16x32_bf16 v[28:31], v[162:165], v[4:7], v[170:173]
	v_mfma_f32_16x16x32_bf16 v[20:23], v[0:3], v[4:7], v[174:177]
	v_mfma_f32_16x16x32_bf16 v[16:19], v[182:185], v[4:7], v[102:105]
	v_mfma_f32_16x16x32_bf16 v[12:15], v[178:181], v[186:189], v[94:97]
	v_mfma_f32_16x16x32_bf16 v[8:11], v[162:165], v[186:189], v[98:101]
	v_mfma_f32_16x16x32_bf16 v[4:7], v[0:3], v[186:189], v[142:145]
	v_mfma_f32_16x16x32_bf16 v[0:3], v[182:185], v[186:189], v[106:109]
	s_cbranch_scc0 .LBB0_454
	s_and_b32 s12, s16, 7
	s_lshl_b32 s12, s12, 3
	s_bfe_u32 s13, s16, 0x30003
	s_or_b32 s12, s12, s13
	s_and_b32 s13, s16, 0xffffffc0
	s_or_b32 s13, s12, s13
	s_ashr_i32 s1, s13, 31
	s_lshr_b32 s1, s1, 29
	s_add_i32 s1, s13, s1
	s_lshl_b32 s5, s1, 4
	s_and_b32 s8, s5, 0xffffff80
	s_and_b32 s1, s1, 0x1fffff8
	s_sub_i32 s1, s13, s1
	s_ashr_i32 s9, s8, 31
	s_lshl_b32 s10, s1, 7
	s_lshl_b64 s[8:9], s[8:9], 11
	v_readlane_b32 s12, v245, 60
	v_readlane_b32 s13, v245, 61
	s_add_u32 s8, s12, s8
	s_addc_u32 s9, s13, s9
	s_ashr_i32 s11, s10, 31
	s_lshl_b64 s[10:11], s[10:11], 11
	s_add_u32 s10, s14, s10
	v_readfirstlane_b32 s1, v149
	s_addc_u32 s11, s15, s11
	s_mov_b32 m0, s1
	v_readfirstlane_b32 s1, v119
	global_load_lds_dwordx4 v126, s[8:9]
	v_lshl_add_u64 v[94:95], v[64:65], 1, s[10:11]
	s_mov_b32 m0, s1
	v_readfirstlane_b32 s1, v120
	global_load_lds_dwordx4 v[94:95], off
	s_mov_b32 m0, s1
	v_readfirstlane_b32 s1, v121
	global_load_lds_dwordx4 v127, s[8:9]
	v_lshl_add_u64 v[94:95], v[66:67], 1, s[10:11]
	s_mov_b32 m0, s1
	v_readfirstlane_b32 s1, v122
	global_load_lds_dwordx4 v[94:95], off
	s_mov_b32 m0, s1
	v_readfirstlane_b32 s1, v123
	global_load_lds_dwordx4 v128, s[8:9]
	v_lshl_add_u64 v[94:95], v[68:69], 1, s[10:11]
	s_mov_b32 m0, s1
	v_readfirstlane_b32 s1, v124
	global_load_lds_dwordx4 v[94:95], off
	s_mov_b32 m0, s1
	v_readfirstlane_b32 s1, v125
	global_load_lds_dwordx4 v129, s[8:9]
	v_lshl_add_u64 v[94:95], v[70:71], 1, s[10:11]
	s_mov_b32 m0, s1
	s_nop 0
	global_load_lds_dwordx4 v[94:95], off
	s_branch .LBB0_454

; template <class Epi>
; __device__ __forceinline__ void gemm_tile(const bf16_t* __restrict__ A, const bf16_t* __restrict__ Bt, int K, int row0, int col0, const Epi& epi, char* smem,
;                                           bool prefetched, bool nvalid, int nrow0, int ncol0) {
;     ...
;         if (kt + 1 < nk) GLDS_STAGE(cur ^ 1, pA, pB, kt + 1);
;         const char* cb = smem + cur * 2 * TILE_B;
; #pragma unroll
;         for (int ks = 0; ks < 2; ++ks) {
;             bf16x8 a[4], b[4];
; #pragma unroll
;             for (int m = 0; m < 4; ++m) a[m] = *(const bf16x8*)(cb + offA[m][ks]);
; #pragma unroll
;             for (int n = 0; n < 4; ++n) b[n] = *(const bf16x8*)(cb + offB[n][ks]);
.LBB0_563:
	v_readfirstlane_b32 s98, v110
	v_readfirstlane_b32 s99, v111
	v_readfirstlane_b32 s10, v118
	v_readfirstlane_b32 s100, v124
	v_readfirstlane_b32 s101, v125
	v_readfirstlane_b32 s17, v149
	s_nop 3
	s_sub_u32 s18, s10, s98
	s_and_b32 s98, s98, 0xffffff80
	s_and_b32 s100, s100, 0xffffff80
	s_nop 1
	v_subrev_u32_e32 v254, s98, v110
	v_subrev_u32_e32 v255, s100, v124
	s_add_i32 s13, s17, 0x8000
	s_mov_b32 m0, s13
	s_nop 0
	global_load_lds_dwordx4 v254, s[98:99]
	s_add_i32 m0, s13, 0x1000
	s_add_u32 s10, s98, s18
	s_addc_u32 s11, s99, 0
	global_load_lds_dwordx4 v254, s[10:11]
	s_add_i32 m0, s13, 0x2000
	s_add_u32 s10, s10, s18
	s_addc_u32 s11, s11, 0
	global_load_lds_dwordx4 v254, s[10:11]
	s_add_i32 m0, s13, 0x3000
	s_add_u32 s10, s10, s18
	s_addc_u32 s11, s11, 0
	global_load_lds_dwordx4 v254, s[10:11]
	s_add_u32 s98, s98, 0x80
	s_addc_u32 s99, s99, 0
	ds_read_b128 v[192:195], v85
	ds_read_b128 v[118:121], v142 offset:16384
	ds_read_b128 v[122:125], v142 offset:16896
	ds_read_b128 v[126:129], v142 offset:20480
	ds_read_b128 v[172:175], v142 offset:20992
	ds_read_b128 v[196:199], v85 offset:2048
	ds_read_b128 v[246:249], v85 offset:4096
	ds_read_b128 v[250:253], v85 offset:6144
	s_setprio 1

; __device__ __forceinline__ f32x4 mfma16(bf16x8 a, bf16x8 b, f32x4 c) { return __builtin_amdgcn_mfma_f32_16x16x32_bf16(a, b, c, 0, 0, 0); }
; template <class Epi>
; __device__ __forceinline__ void gemm_tile(const bf16_t* __restrict__ A, const bf16_t* __restrict__ Bt, int K, int row0, int col0, const Epi& epi, char* smem,
;                                           bool prefetched, bool nvalid, int nrow0, int ncol0) {
;     ...
;     for (int kt = 0; kt < nk; ++kt) {
;         const int cur = kt & 1;
;         if (kt + 1 < nk) GLDS_STAGE(cur ^ 1, pA, pB, kt + 1);
;         const char* cb = smem + cur * 2 * TILE_B;
; #pragma unroll
;         for (int ks = 0; ks < 2; ++ks) {
;             bf16x8 a[4], b[4];
; #pragma unroll
;             for (int m = 0; m < 4; ++m) a[m] = *(const bf16x8*)(cb + offA[m][ks]);
; #pragma unroll
;             for (int n = 0; n < 4; ++n) b[n] = *(const bf16x8*)(cb + offB[n][ks]);
; #pragma unroll
;             for (int m = 0; m < 4; ++m)
; #pragma unroll
;                 for (int n = 0; n < 4; ++n) acc[m][n] = mfma16(b[n], a[m], acc[m][n]);
;         }
;         asm volatile("s_waitcnt vmcnt(0)" ::: "memory");
;         __syncthreads();
;     }
;     if (nvalid) { const bf16_t* qA = A + (size_t)nrow0 * K; const bf16_t* qB = Bt + (size_t)ncol0 * K; GLDS_STAGE(0, qA, qB, 0); }
; template <class Epi>
; __device__ __forceinline__ void gemm_phase(const bf16_t* A, const bf16_t* Bt, int M, int N, int K, const Epi& epi, char* smem) {
;     ...
;     for (int i = blockIdx.x; i < ntiles; i += G) {
;         const int j = i + G; const bool nv = j < ntiles;
;         gemm_tile(A, Bt, K, (i / nN) << 7, (i % nN) << 7, epi, smem, pre, nv, (j / nN) << 7, (j % nN) << 7);
;         pre = nv;
.Lgk_tail_563:
	s_setprio 0
	v_mfma_f32_16x16x32_bf16 v[32:35], v[176:179], v[246:249], v[32:35]
	v_mfma_f32_16x16x32_bf16 v[36:39], v[180:183], v[246:249], v[36:39]
	v_mfma_f32_16x16x32_bf16 v[40:43], v[184:187], v[246:249], v[40:43]
	v_mfma_f32_16x16x32_bf16 v[44:47], v[188:191], v[246:249], v[44:47]
	v_mfma_f32_16x16x32_bf16 v[48:51], v[176:179], v[250:253], v[48:51]
	v_mfma_f32_16x16x32_bf16 v[52:55], v[180:183], v[250:253], v[52:55]
	v_mfma_f32_16x16x32_bf16 v[56:59], v[184:187], v[250:253], v[56:59]
	v_mfma_f32_16x16x32_bf16 v[60:63], v[188:191], v[250:253], v[60:63]
	ds_read_b128 v[118:121], v142 offset:49152
	ds_read_b128 v[122:125], v85 offset:32768
	ds_read_b128 v[126:129], v142 offset:49664
	ds_read_b128 v[172:175], v142 offset:53248
	ds_read_b128 v[176:179], v142 offset:53760
	s_add_i32 s16, s16, s58
	s_waitcnt lgkmcnt(3)
	v_mfma_f32_16x16x32_bf16 v[0:3], v[118:121], v[122:125], v[0:3]
	s_cmpk_gt_i32 s16, 0x1fff
	s_cselect_b64 s[6:7], -1, 0
	s_cmpk_lt_i32 s16, 0x2000
	s_waitcnt lgkmcnt(2)
	v_mfma_f32_16x16x32_bf16 v[4:7], v[126:129], v[122:125], v[4:7]
	ds_read_b128 v[192:195], v141 offset:49152
	ds_read_b128 v[196:199], v141 offset:53760
	s_waitcnt lgkmcnt(3)
	v_mfma_f32_16x16x32_bf16 v[8:11], v[172:175], v[122:125], v[8:11]
	s_waitcnt lgkmcnt(2)
	v_mfma_f32_16x16x32_bf16 v[12:15], v[176:179], v[122:125], v[12:15]
	ds_read_b128 v[122:125], v85 offset:34816
	s_waitcnt lgkmcnt(0)
	v_mfma_f32_16x16x32_bf16 v[16:19], v[118:121], v[122:125], v[16:19]
	v_mfma_f32_16x16x32_bf16 v[20:23], v[126:129], v[122:125], v[20:23]
	v_mfma_f32_16x16x32_bf16 v[24:27], v[172:175], v[122:125], v[24:27]
	v_mfma_f32_16x16x32_bf16 v[28:31], v[176:179], v[122:125], v[28:31]
	ds_read_b128 v[122:125], v85 offset:36864
	s_waitcnt lgkmcnt(0)
	v_mfma_f32_16x16x32_bf16 v[180:183], v[118:121], v[122:125], v[32:35]
	s_nop 2
	ds_read_b128 v[32:35], v85 offset:38912
	v_mfma_f32_16x16x32_bf16 v[184:187], v[126:129], v[122:125], v[36:39]
	v_mfma_f32_16x16x32_bf16 v[188:191], v[172:175], v[122:125], v[40:43]
	v_mfma_f32_16x16x32_bf16 v[122:125], v[176:179], v[122:125], v[44:47]
	s_waitcnt lgkmcnt(0)
	v_mfma_f32_16x16x32_bf16 v[118:121], v[118:121], v[32:35], v[48:51]
	v_mfma_f32_16x16x32_bf16 v[126:129], v[126:129], v[32:35], v[52:55]
	v_mfma_f32_16x16x32_bf16 v[172:175], v[172:175], v[32:35], v[56:59]
	v_mfma_f32_16x16x32_bf16 v[176:179], v[176:179], v[32:35], v[60:63]
	ds_read_b128 v[32:35], v87 offset:32768
	s_waitcnt lgkmcnt(0)
	v_mfma_f32_16x16x32_bf16 v[56:59], v[192:195], v[32:35], v[0:3]
	s_nop 2
	ds_read_b128 v[0:3], v141 offset:49664
	s_waitcnt lgkmcnt(0)
	v_mfma_f32_16x16x32_bf16 v[60:63], v[0:3], v[32:35], v[4:7]
	s_nop 2
	ds_read_b128 v[4:7], v141 offset:53248
	s_waitcnt lgkmcnt(0)
	v_mfma_f32_16x16x32_bf16 v[48:51], v[4:7], v[32:35], v[8:11]
	s_nop 2
	ds_read_b128 v[8:11], v87 offset:34816
	v_mfma_f32_16x16x32_bf16 v[52:55], v[196:199], v[32:35], v[12:15]
	s_waitcnt lgkmcnt(0)
	v_mfma_f32_16x16x32_bf16 v[44:47], v[192:195], v[8:11], v[16:19]
	v_mfma_f32_16x16x32_bf16 v[40:43], v[0:3], v[8:11], v[20:23]
	v_mfma_f32_16x16x32_bf16 v[36:39], v[4:7], v[8:11], v[24:27]
	v_mfma_f32_16x16x32_bf16 v[32:35], v[196:199], v[8:11], v[28:31]
	ds_read_b128 v[8:11], v87 offset:36864
	s_waitcnt lgkmcnt(0)
	v_mfma_f32_16x16x32_bf16 v[16:19], v[196:199], v[8:11], v[122:125]
	s_nop 2
	ds_read_b128 v[122:125], v87 offset:38912
	s_waitcnt vmcnt(0)
	v_mfma_f32_16x16x32_bf16 v[28:31], v[192:195], v[8:11], v[180:183]
	s_waitcnt lgkmcnt(0)
	s_barrier
	v_mfma_f32_16x16x32_bf16 v[24:27], v[0:3], v[8:11], v[184:187]
	v_mfma_f32_16x16x32_bf16 v[20:23], v[4:7], v[8:11], v[188:191]
	v_mfma_f32_16x16x32_bf16 v[8:11], v[192:195], v[122:125], v[118:121]
	v_mfma_f32_16x16x32_bf16 v[12:15], v[0:3], v[122:125], v[126:129]
	v_mfma_f32_16x16x32_bf16 v[0:3], v[4:7], v[122:125], v[172:175]
	v_mfma_f32_16x16x32_bf16 v[4:7], v[196:199], v[122:125], v[176:179]
	s_cbranch_scc0 .LBB0_557
	s_and_b32 s10, s16, 7
	s_lshl_b32 s10, s10, 3
	s_bfe_u32 s11, s16, 0x30006
	s_or_b32 s10, s10, s11
	s_lshr_b32 s11, s16, 11
	s_lshl_b32 s11, s11, 6
	s_or_b32 s10, s10, s11
	s_lshl_b32 s10, s10, 5
	s_bfe_u32 s11, s16, 0x30003
	s_or_b32 s10, s10, s11
	s_bfe_u32 s11, s16, 0x20009
	s_lshl_b32 s11, s11, 3
	s_or_b32 s11, s10, s11
	s_ashr_i32 s8, s11, 31
	s_lshr_b32 s8, s8, 27
	s_add_i32 s9, s11, s8
	s_lshl_b32 s8, s9, 2
	s_and_b32 s9, s9, 0x1ffffe0
	s_and_b32 s8, s8, 0xffffff80
	s_sub_i32 s9, s11, s9
	s_lshl_b32 s10, s9, 7
	s_ashr_i32 s9, s8, 31
	s_lshl_b64 s[8:9], s[8:9], 11
	v_readlane_b32 s11, v245, 53
	s_add_u32 s8, s11, s8
	v_readlane_b32 s11, v245, 54
	s_addc_u32 s9, s11, s9
	s_ashr_i32 s11, s10, 31
	s_lshl_b64 s[10:11], s[10:11], 11
	s_add_u32 s10, s14, s10
	v_readfirstlane_b32 s12, v149
	s_addc_u32 s11, s15, s11
	s_mov_b32 m0, s12
	v_readfirstlane_b32 s12, v143
	global_load_lds_dwordx4 v168, s[8:9]
	v_lshl_add_u64 v[110:111], v[64:65], 1, s[10:11]
	s_mov_b32 m0, s12
	v_readfirstlane_b32 s12, v144
	global_load_lds_dwordx4 v[110:111], off
	s_mov_b32 m0, s12
	v_readfirstlane_b32 s12, v145
	global_load_lds_dwordx4 v169, s[8:9]
	v_lshl_add_u64 v[110:111], v[66:67], 1, s[10:11]
	s_mov_b32 m0, s12
	v_readfirstlane_b32 s12, v162
	global_load_lds_dwordx4 v[110:111], off
	s_mov_b32 m0, s12
	v_readfirstlane_b32 s12, v163
	global_load_lds_dwordx4 v170, s[8:9]
	v_lshl_add_u64 v[110:111], v[68:69], 1, s[10:11]
	s_mov_b32 m0, s12
	v_readfirstlane_b32 s12, v164
	global_load_lds_dwordx4 v[110:111], off
	s_mov_b32 m0, s12
	v_lshl_add_u64 v[110:111], v[70:71], 1, s[10:11]
	global_load_lds_dwordx4 v171, s[8:9]
	v_readfirstlane_b32 s8, v165
	s_mov_b32 m0, s8
	s_nop 0
	global_load_lds_dwordx4 v[110:111], off
	s_branch .LBB0_557

; template <class Epi>
; __device__ __forceinline__ void gemm_tile(const bf16_t* __restrict__ A, const bf16_t* __restrict__ Bt, int K, int row0, int col0, const Epi& epi, char* smem,
;                                           bool prefetched, bool nvalid, int nrow0, int ncol0) {
;     ...
;         if (kt + 1 < nk) GLDS_STAGE(cur ^ 1, pA, pB, kt + 1);
;         const char* cb = smem + cur * 2 * TILE_B;
; #pragma unroll
;         for (int ks = 0; ks < 2; ++ks) {
;             bf16x8 a[4], b[4];
; #pragma unroll
;             for (int m = 0; m < 4; ++m) a[m] = *(const bf16x8*)(cb + offA[m][ks]);
; #pragma unroll
;             for (int n = 0; n < 4; ++n) b[n] = *(const bf16x8*)(cb + offB[n][ks]);
.LBB0_619:
	v_readfirstlane_b32 s98, v92
	v_readfirstlane_b32 s99, v93
	v_readfirstlane_b32 s8, v94
	v_readfirstlane_b32 s100, v100
	v_readfirstlane_b32 s101, v101
	v_readfirstlane_b32 s12, v149
	s_nop 3
	s_sub_u32 s13, s8, s98
	s_and_b32 s98, s98, 0xffffff80
	s_and_b32 s100, s100, 0xffffff80
	s_nop 1
	v_subrev_u32_e32 v254, s98, v92
	v_subrev_u32_e32 v255, s100, v100
	s_add_i32 s11, s12, 0x8000
	s_mov_b32 m0, s11
	s_nop 0
	global_load_lds_dwordx4 v254, s[98:99]
	s_add_i32 m0, s11, 0x1000
	s_add_u32 s8, s98, s13
	s_addc_u32 s9, s99, 0
	global_load_lds_dwordx4 v254, s[8:9]
	s_add_i32 m0, s11, 0x2000
	s_add_u32 s8, s8, s13
	s_addc_u32 s9, s9, 0
	global_load_lds_dwordx4 v254, s[8:9]
	s_add_i32 m0, s11, 0x3000
	s_add_u32 s8, s8, s13
	s_addc_u32 s9, s9, 0
	global_load_lds_dwordx4 v254, s[8:9]
	s_add_u32 s98, s98, 0x80
	s_addc_u32 s99, s99, 0
	ds_read_b128 v[174:177], v108
	ds_read_b128 v[92:95], v110 offset:16384
	ds_read_b128 v[96:99], v110 offset:16896
	ds_read_b128 v[100:103], v110 offset:20480
	ds_read_b128 v[104:107], v110 offset:20992
	ds_read_b128 v[178:181], v108 offset:2048
	ds_read_b128 v[246:249], v108 offset:4096
	ds_read_b128 v[250:253], v108 offset:6144
	s_setprio 1

; __device__ __forceinline__ f32x4 mfma16(bf16x8 a, bf16x8 b, f32x4 c) { return __builtin_amdgcn_mfma_f32_16x16x32_bf16(a, b, c, 0, 0, 0); }
; template <class Epi>
; __device__ __forceinline__ void gemm_tile(const bf16_t* __restrict__ A, const bf16_t* __restrict__ Bt, int K, int row0, int col0, const Epi& epi, char* smem,
;                                           bool prefetched, bool nvalid, int nrow0, int ncol0) {
;     ...
;     for (int kt = 0; kt < nk; ++kt) {
;         const int cur = kt & 1;
;         if (kt + 1 < nk) GLDS_STAGE(cur ^ 1, pA, pB, kt + 1);
;         const char* cb = smem + cur * 2 * TILE_B;
; #pragma unroll
;         for (int ks = 0; ks < 2; ++ks) {
;             bf16x8 a[4], b[4];
; #pragma unroll
;             for (int m = 0; m < 4; ++m) a[m] = *(const bf16x8*)(cb + offA[m][ks]);
; #pragma unroll
;             for (int n = 0; n < 4; ++n) b[n] = *(const bf16x8*)(cb + offB[n][ks]);
; #pragma unroll
;             for (int m = 0; m < 4; ++m)
; #pragma unroll
;                 for (int n = 0; n < 4; ++n) acc[m][n] = mfma16(b[n], a[m], acc[m][n]);
;         }
;         asm volatile("s_waitcnt vmcnt(0)" ::: "memory");
;         __syncthreads();
;     }
;     if (nvalid) { const bf16_t* qA = A + (size_t)nrow0 * K; const bf16_t* qB = Bt + (size_t)ncol0 * K; GLDS_STAGE(0, qA, qB, 0); }
; template <class Epi>
; __device__ __forceinline__ void gemm_phase(const bf16_t* A, const bf16_t* Bt, int M, int N, int K, const Epi& epi, char* smem) {
;     ...
;     for (int i = blockIdx.x; i < ntiles; i += G) {
;         const int j = i + G; const bool nv = j < ntiles;
;         gemm_tile(A, Bt, K, (i / nN) << 7, (i % nN) << 7, epi, smem, pre, nv, (j / nN) << 7, (j % nN) << 7);
;         pre = nv;
.Lgk_tail_619:
	s_setprio 0
	v_mfma_f32_16x16x32_bf16 v[32:35], v[142:145], v[246:249], v[32:35]
	v_mfma_f32_16x16x32_bf16 v[36:39], v[162:165], v[246:249], v[36:39]
	v_mfma_f32_16x16x32_bf16 v[40:43], v[166:169], v[246:249], v[40:43]
	v_mfma_f32_16x16x32_bf16 v[44:47], v[170:173], v[246:249], v[44:47]
	v_mfma_f32_16x16x32_bf16 v[48:51], v[142:145], v[250:253], v[48:51]
	v_mfma_f32_16x16x32_bf16 v[52:55], v[162:165], v[250:253], v[52:55]
	v_mfma_f32_16x16x32_bf16 v[56:59], v[166:169], v[250:253], v[56:59]
	v_mfma_f32_16x16x32_bf16 v[60:63], v[170:173], v[250:253], v[60:63]
	ds_read_b128 v[92:95], v110 offset:49152
	ds_read_b128 v[96:99], v110 offset:49664
	ds_read_b128 v[100:103], v108 offset:32768
	ds_read_b128 v[104:107], v108 offset:34816
	ds_read_b128 v[142:145], v110 offset:53248
	ds_read_b128 v[162:165], v110 offset:53760
	s_add_i32 s16, s16, s58
	s_waitcnt lgkmcnt(3)
	v_mfma_f32_16x16x32_bf16 v[0:3], v[92:95], v[100:103], v[0:3]
	s_cmpk_gt_i32 s16, 0x7ff
	s_cselect_b64 s[6:7], -1, 0
	s_cmpk_lt_i32 s16, 0x800
	v_mfma_f32_16x16x32_bf16 v[4:7], v[96:99], v[100:103], v[4:7]
	s_waitcnt lgkmcnt(1)
	v_mfma_f32_16x16x32_bf16 v[8:11], v[142:145], v[100:103], v[8:11]
	s_waitcnt lgkmcnt(0)
	v_mfma_f32_16x16x32_bf16 v[12:15], v[162:165], v[100:103], v[12:15]
	v_mfma_f32_16x16x32_bf16 v[16:19], v[92:95], v[104:107], v[16:19]
	v_mfma_f32_16x16x32_bf16 v[20:23], v[96:99], v[104:107], v[20:23]
	v_mfma_f32_16x16x32_bf16 v[24:27], v[142:145], v[104:107], v[24:27]
	v_mfma_f32_16x16x32_bf16 v[28:31], v[162:165], v[104:107], v[28:31]
	ds_read_b128 v[100:103], v108 offset:36864
	ds_read_b128 v[104:107], v108 offset:38912
	ds_read_b128 v[178:181], v111 offset:49152
	s_waitcnt lgkmcnt(2)
	v_mfma_f32_16x16x32_bf16 v[166:169], v[92:95], v[100:103], v[32:35]
	v_mfma_f32_16x16x32_bf16 v[170:173], v[96:99], v[100:103], v[36:39]
	v_mfma_f32_16x16x32_bf16 v[174:177], v[142:145], v[100:103], v[40:43]
	v_mfma_f32_16x16x32_bf16 v[100:103], v[162:165], v[100:103], v[44:47]
	s_waitcnt lgkmcnt(1)
	v_mfma_f32_16x16x32_bf16 v[92:95], v[92:95], v[104:107], v[48:51]
	v_mfma_f32_16x16x32_bf16 v[96:99], v[96:99], v[104:107], v[52:55]
	v_mfma_f32_16x16x32_bf16 v[142:145], v[142:145], v[104:107], v[56:59]
	v_mfma_f32_16x16x32_bf16 v[104:107], v[162:165], v[104:107], v[60:63]
	ds_read_b128 v[162:165], v111 offset:49664
	ds_read_b128 v[32:35], v109 offset:32768
	ds_read_b128 v[36:39], v109 offset:34816
	ds_read_b128 v[182:185], v111 offset:53760
	s_waitcnt lgkmcnt(2)
	v_mfma_f32_16x16x32_bf16 v[52:55], v[178:181], v[32:35], v[0:3]
	s_nop 2
	ds_read_b128 v[0:3], v111 offset:53248
	v_mfma_f32_16x16x32_bf16 v[56:59], v[162:165], v[32:35], v[4:7]
	s_nop 2
	ds_read_b128 v[4:7], v109 offset:36864
	ds_read_b128 v[186:189], v109 offset:38912
	s_waitcnt vmcnt(0)
	s_waitcnt lgkmcnt(0)
	v_mfma_f32_16x16x32_bf16 v[60:63], v[0:3], v[32:35], v[8:11]
	s_barrier
	v_mfma_f32_16x16x32_bf16 v[48:51], v[182:185], v[32:35], v[12:15]
	v_mfma_f32_16x16x32_bf16 v[44:47], v[178:181], v[36:39], v[16:19]
	v_mfma_f32_16x16x32_bf16 v[40:43], v[162:165], v[36:39], v[20:23]
	v_mfma_f32_16x16x32_bf16 v[32:35], v[0:3], v[36:39], v[24:27]
	v_mfma_f32_16x16x32_bf16 v[24:27], v[182:185], v[36:39], v[28:31]
	v_mfma_f32_16x16x32_bf16 v[36:39], v[178:181], v[4:7], v[166:169]
	v_mfma_f32_16x16x32_bf16 v[28:31], v[162:165], v[4:7], v[170:173]
	v_mfma_f32_16x16x32_bf16 v[20:23], v[0:3], v[4:7], v[174:177]
	v_mfma_f32_16x16x32_bf16 v[16:19], v[182:185], v[4:7], v[100:103]
	v_mfma_f32_16x16x32_bf16 v[12:15], v[178:181], v[186:189], v[92:95]
	v_mfma_f32_16x16x32_bf16 v[8:11], v[162:165], v[186:189], v[96:99]
	v_mfma_f32_16x16x32_bf16 v[4:7], v[0:3], v[186:189], v[142:145]
	v_mfma_f32_16x16x32_bf16 v[0:3], v[182:185], v[186:189], v[104:107]
	s_cbranch_scc0 .LBB0_613
	s_and_b32 s12, s16, 7
	s_lshl_b32 s12, s12, 3
	s_bfe_u32 s13, s16, 0x30003
	s_or_b32 s12, s12, s13
	s_and_b32 s13, s16, 0xffffffc0
	s_or_b32 s13, s12, s13
	s_ashr_i32 s1, s13, 31
	s_lshr_b32 s1, s1, 29
	s_add_i32 s1, s13, s1
	s_lshl_b32 s3, s1, 4
	s_and_b32 s8, s3, 0xffffff80
	s_and_b32 s1, s1, 0x1fffff8
	s_sub_i32 s1, s13, s1
	s_ashr_i32 s9, s8, 31
	s_lshl_b32 s10, s1, 7
	s_lshl_b64 s[8:9], s[8:9], 13
	v_readlane_b32 s12, v245, 55
	v_readlane_b32 s13, v245, 56
	s_add_u32 s8, s12, s8
	s_addc_u32 s9, s13, s9
	s_ashr_i32 s11, s10, 31
	s_lshl_b64 s[10:11], s[10:11], 13
	s_add_u32 s10, s14, s10
	v_readfirstlane_b32 s1, v149
	s_addc_u32 s11, s15, s11
	s_mov_b32 m0, s1
	v_readfirstlane_b32 s1, v118
	global_load_lds_dwordx4 v125, s[8:9]
	v_lshl_add_u64 v[92:93], v[64:65], 1, s[10:11]
	s_mov_b32 m0, s1
	v_readfirstlane_b32 s1, v119
	global_load_lds_dwordx4 v[92:93], off
	s_mov_b32 m0, s1
	v_readfirstlane_b32 s1, v120
	global_load_lds_dwordx4 v126, s[8:9]
	v_lshl_add_u64 v[92:93], v[66:67], 1, s[10:11]
	s_mov_b32 m0, s1
	v_readfirstlane_b32 s1, v121
	global_load_lds_dwordx4 v[92:93], off
	s_mov_b32 m0, s1
	v_readfirstlane_b32 s1, v122
	global_load_lds_dwordx4 v127, s[8:9]
	v_lshl_add_u64 v[92:93], v[68:69], 1, s[10:11]
	s_mov_b32 m0, s1
	v_readfirstlane_b32 s1, v123
	global_load_lds_dwordx4 v[92:93], off
	s_mov_b32 m0, s1
	v_readfirstlane_b32 s1, v124
	global_load_lds_dwordx4 v128, s[8:9]
	v_lshl_add_u64 v[92:93], v[70:71], 1, s[10:11]
	s_mov_b32 m0, s1
	s_nop 0
	global_load_lds_dwordx4 v[92:93], off
	s_branch .LBB0_613

; template <class Epi>
; __device__ __forceinline__ void gemm_tile(const bf16_t* __restrict__ A, const bf16_t* __restrict__ Bt, int K, int row0, int col0, const Epi& epi, char* smem,
;                                           bool prefetched, bool nvalid, int nrow0, int ncol0) {
;     ...
;         if (kt + 1 < nk) GLDS_STAGE(cur ^ 1, pA, pB, kt + 1);
;         const char* cb = smem + cur * 2 * TILE_B;
; #pragma unroll
;         for (int ks = 0; ks < 2; ++ks) {
;             bf16x8 a[4], b[4];
; #pragma unroll
;             for (int m = 0; m < 4; ++m) a[m] = *(const bf16x8*)(cb + offA[m][ks]);
; #pragma unroll
;             for (int n = 0; n < 4; ++n) b[n] = *(const bf16x8*)(cb + offB[n][ks]);
.LBB0_723:
	v_readfirstlane_b32 s98, v64
	v_readfirstlane_b32 s99, v65
	v_readfirstlane_b32 s12, v66
	v_readfirstlane_b32 s100, v72
	v_readfirstlane_b32 s101, v73
	v_readfirstlane_b32 s15, v149
	s_nop 3
	s_sub_u32 s16, s12, s98
	s_and_b32 s98, s98, 0xffffff80
	s_and_b32 s100, s100, 0xffffff80
	s_nop 1
	v_subrev_u32_e32 v254, s98, v64
	v_subrev_u32_e32 v255, s100, v72
	s_add_i32 s14, s15, 0x8000
	s_mov_b32 m0, s14
	s_nop 0
	global_load_lds_dwordx4 v254, s[98:99]
	s_add_i32 m0, s14, 0x1000
	s_add_u32 s12, s98, s16
	s_addc_u32 s13, s99, 0
	global_load_lds_dwordx4 v254, s[12:13]
	s_add_i32 m0, s14, 0x2000
	s_add_u32 s12, s12, s16
	s_addc_u32 s13, s13, 0
	global_load_lds_dwordx4 v254, s[12:13]
	s_add_i32 m0, s14, 0x3000
	s_add_u32 s12, s12, s16
	s_addc_u32 s13, s13, 0
	global_load_lds_dwordx4 v254, s[12:13]
	s_add_u32 s98, s98, 0x80
	s_addc_u32 s99, s99, 0
	ds_read_b128 v[188:191], v137
	ds_read_b128 v[64:67], v143 offset:16384
	ds_read_b128 v[68:71], v143 offset:16896
	ds_read_b128 v[72:75], v143 offset:20480
	ds_read_b128 v[76:79], v143 offset:20992
	ds_read_b128 v[192:195], v137 offset:2048
	ds_read_b128 v[246:249], v137 offset:4096
	ds_read_b128 v[250:253], v137 offset:6144
	s_setprio 1

; __device__ __forceinline__ f32x4 mfma16(bf16x8 a, bf16x8 b, f32x4 c) { return __builtin_amdgcn_mfma_f32_16x16x32_bf16(a, b, c, 0, 0, 0); }
; template <class Epi>
; __device__ __forceinline__ void gemm_tile(const bf16_t* __restrict__ A, const bf16_t* __restrict__ Bt, int K, int row0, int col0, const Epi& epi, char* smem,
;                                           bool prefetched, bool nvalid, int nrow0, int ncol0) {
;     ...
;     for (int kt = 0; kt < nk; ++kt) {
;         const int cur = kt & 1;
;         if (kt + 1 < nk) GLDS_STAGE(cur ^ 1, pA, pB, kt + 1);
;         const char* cb = smem + cur * 2 * TILE_B;
; #pragma unroll
;         for (int ks = 0; ks < 2; ++ks) {
;             bf16x8 a[4], b[4];
; #pragma unroll
;             for (int m = 0; m < 4; ++m) a[m] = *(const bf16x8*)(cb + offA[m][ks]);
; #pragma unroll
;             for (int n = 0; n < 4; ++n) b[n] = *(const bf16x8*)(cb + offB[n][ks]);
; #pragma unroll
;             for (int m = 0; m < 4; ++m)
; #pragma unroll
;                 for (int n = 0; n < 4; ++n) acc[m][n] = mfma16(b[n], a[m], acc[m][n]);
;         }
;         asm volatile("s_waitcnt vmcnt(0)" ::: "memory");
;         __syncthreads();
;     }
;     if (nvalid) { const bf16_t* qA = A + (size_t)nrow0 * K; const bf16_t* qB = Bt + (size_t)ncol0 * K; GLDS_STAGE(0, qA, qB, 0); }
; template <class Epi>
; __device__ __forceinline__ void gemm_phase(const bf16_t* A, const bf16_t* Bt, int M, int N, int K, const Epi& epi, char* smem) {
;     ...
;     for (int i = blockIdx.x; i < ntiles; i += G) {
;         const int j = i + G; const bool nv = j < ntiles;
;         gemm_tile(A, Bt, K, (i / nN) << 7, (i % nN) << 7, epi, smem, pre, nv, (j / nN) << 7, (j % nN) << 7);
;         pre = nv;
.Lgk_tail_723:
	s_setprio 0
	v_mfma_f32_16x16x32_bf16 v[32:35], v[80:83], v[246:249], v[32:35]
	v_mfma_f32_16x16x32_bf16 v[36:39], v[128:131], v[246:249], v[36:39]
	v_mfma_f32_16x16x32_bf16 v[40:43], v[180:183], v[246:249], v[40:43]
	v_mfma_f32_16x16x32_bf16 v[44:47], v[184:187], v[246:249], v[44:47]
	v_mfma_f32_16x16x32_bf16 v[48:51], v[80:83], v[250:253], v[48:51]
	v_mfma_f32_16x16x32_bf16 v[52:55], v[128:131], v[250:253], v[52:55]
	v_mfma_f32_16x16x32_bf16 v[56:59], v[180:183], v[250:253], v[56:59]
	v_mfma_f32_16x16x32_bf16 v[60:63], v[184:187], v[250:253], v[60:63]
	ds_read_b128 v[64:67], v143 offset:49152
	ds_read_b128 v[68:71], v137 offset:32768
	ds_read_b128 v[72:75], v143 offset:49664
	ds_read_b128 v[76:79], v143 offset:53248
	ds_read_b128 v[80:83], v143 offset:53760
	s_add_i32 s24, s24, s58
	s_waitcnt lgkmcnt(3)
	v_mfma_f32_16x16x32_bf16 v[0:3], v[64:67], v[68:71], v[0:3]
	s_cmpk_gt_i32 s24, 0xfff
	s_cselect_b64 s[10:11], -1, 0
	s_cmpk_lt_i32 s24, 0x1000
	s_waitcnt lgkmcnt(2)
	v_mfma_f32_16x16x32_bf16 v[4:7], v[72:75], v[68:71], v[4:7]
	ds_read_b128 v[188:191], v142 offset:49152
	ds_read_b128 v[192:195], v142 offset:53760
	s_waitcnt lgkmcnt(3)
	v_mfma_f32_16x16x32_bf16 v[8:11], v[76:79], v[68:71], v[8:11]
	s_waitcnt lgkmcnt(2)
	v_mfma_f32_16x16x32_bf16 v[12:15], v[80:83], v[68:71], v[12:15]
	ds_read_b128 v[68:71], v137 offset:34816
	s_waitcnt lgkmcnt(0)
	v_mfma_f32_16x16x32_bf16 v[16:19], v[64:67], v[68:71], v[16:19]
	v_mfma_f32_16x16x32_bf16 v[20:23], v[72:75], v[68:71], v[20:23]
	v_mfma_f32_16x16x32_bf16 v[24:27], v[76:79], v[68:71], v[24:27]
	v_mfma_f32_16x16x32_bf16 v[28:31], v[80:83], v[68:71], v[28:31]
	ds_read_b128 v[68:71], v137 offset:36864
	s_waitcnt lgkmcnt(0)
	v_mfma_f32_16x16x32_bf16 v[128:131], v[64:67], v[68:71], v[32:35]
	s_nop 2
	ds_read_b128 v[32:35], v137 offset:38912
	v_mfma_f32_16x16x32_bf16 v[180:183], v[72:75], v[68:71], v[36:39]
	v_mfma_f32_16x16x32_bf16 v[184:187], v[76:79], v[68:71], v[40:43]
	v_mfma_f32_16x16x32_bf16 v[68:71], v[80:83], v[68:71], v[44:47]
	s_waitcnt lgkmcnt(0)
	v_mfma_f32_16x16x32_bf16 v[64:67], v[64:67], v[32:35], v[48:51]
	v_mfma_f32_16x16x32_bf16 v[72:75], v[72:75], v[32:35], v[52:55]
	v_mfma_f32_16x16x32_bf16 v[76:79], v[76:79], v[32:35], v[56:59]
	v_mfma_f32_16x16x32_bf16 v[80:83], v[80:83], v[32:35], v[60:63]
	ds_read_b128 v[32:35], v141 offset:32768
	s_waitcnt lgkmcnt(0)
	v_mfma_f32_16x16x32_bf16 v[56:59], v[188:191], v[32:35], v[0:3]
	s_nop 2
	ds_read_b128 v[0:3], v142 offset:49664
	s_waitcnt lgkmcnt(0)
	v_mfma_f32_16x16x32_bf16 v[60:63], v[0:3], v[32:35], v[4:7]
	s_nop 2
	ds_read_b128 v[4:7], v142 offset:53248
	s_waitcnt lgkmcnt(0)
	v_mfma_f32_16x16x32_bf16 v[48:51], v[4:7], v[32:35], v[8:11]
	s_nop 2
	ds_read_b128 v[8:11], v141 offset:34816
	v_mfma_f32_16x16x32_bf16 v[52:55], v[192:195], v[32:35], v[12:15]
	s_waitcnt lgkmcnt(0)
	v_mfma_f32_16x16x32_bf16 v[40:43], v[188:191], v[8:11], v[16:19]
	v_mfma_f32_16x16x32_bf16 v[44:47], v[0:3], v[8:11], v[20:23]
	v_mfma_f32_16x16x32_bf16 v[32:35], v[4:7], v[8:11], v[24:27]
	v_mfma_f32_16x16x32_bf16 v[36:39], v[192:195], v[8:11], v[28:31]
	ds_read_b128 v[8:11], v141 offset:36864
	s_waitcnt lgkmcnt(0)
	v_mfma_f32_16x16x32_bf16 v[20:23], v[192:195], v[8:11], v[68:71]
	s_nop 2
	ds_read_b128 v[68:71], v141 offset:38912
	s_waitcnt vmcnt(0)
	v_mfma_f32_16x16x32_bf16 v[24:27], v[188:191], v[8:11], v[128:131]
	s_waitcnt lgkmcnt(0)
	s_barrier
	v_mfma_f32_16x16x32_bf16 v[28:31], v[0:3], v[8:11], v[180:183]
	v_mfma_f32_16x16x32_bf16 v[16:19], v[4:7], v[8:11], v[184:187]
	v_mfma_f32_16x16x32_bf16 v[8:11], v[188:191], v[68:71], v[64:67]
	v_mfma_f32_16x16x32_bf16 v[12:15], v[0:3], v[68:71], v[72:75]
	v_mfma_f32_16x16x32_bf16 v[0:3], v[4:7], v[68:71], v[76:79]
	v_mfma_f32_16x16x32_bf16 v[4:7], v[192:195], v[68:71], v[80:83]
	s_cbranch_scc0 .LBB0_726
	s_and_b32 s12, s24, 7
	s_lshl_b32 s12, s12, 3
	s_bfe_u32 s13, s24, 0x30006
	s_or_b32 s12, s12, s13
	s_lshr_b32 s13, s24, 10
	s_lshl_b32 s13, s13, 6
	s_or_b32 s12, s12, s13
	s_lshl_b32 s12, s12, 4
	s_bfe_u32 s13, s24, 0x30003
	s_or_b32 s12, s12, s13
	s_bfe_u32 s13, s24, 0x10009
	s_lshl_b32 s13, s13, 3
	s_or_b32 s13, s12, s13
	s_ashr_i32 s0, s13, 31
	s_lshr_b32 s0, s0, 28
	s_add_i32 s1, s13, s0
	s_lshl_b32 s0, s1, 3
	s_and_b32 s1, s1, 0x1fffff0
	s_and_b32 s0, s0, 0xffffff80
	s_sub_i32 s1, s13, s1
	s_lshl_b32 s12, s1, 7
	s_ashr_i32 s1, s0, 31
	s_lshl_b64 s[0:1], s[0:1], 11
	v_readlane_b32 s7, v245, 53
	s_add_u32 s0, s7, s0
	v_readlane_b32 s7, v245, 54
	s_addc_u32 s1, s7, s1
	s_ashr_i32 s13, s12, 31
	s_lshl_b64 s[12:13], s[12:13], 11
	s_add_u32 s12, s3, s12
	v_readfirstlane_b32 s7, v149
	s_addc_u32 s13, s20, s13
	s_mov_b32 m0, s7
	v_readfirstlane_b32 s7, v163
	global_load_lds_dwordx4 v174, s[0:1]
	v_lshl_add_u64 v[64:65], v[84:85], 1, s[12:13]
	s_mov_b32 m0, s7
	v_readfirstlane_b32 s7, v164
	global_load_lds_dwordx4 v[64:65], off
	s_mov_b32 m0, s7
	v_readfirstlane_b32 s7, v165
	global_load_lds_dwordx4 v175, s[0:1]
	v_lshl_add_u64 v[64:65], v[86:87], 1, s[12:13]
	s_mov_b32 m0, s7
	v_readfirstlane_b32 s7, v166
	global_load_lds_dwordx4 v[64:65], off
	s_mov_b32 m0, s7
	v_readfirstlane_b32 s7, v170
	global_load_lds_dwordx4 v176, s[0:1]
	v_lshl_add_u64 v[64:65], v[88:89], 1, s[12:13]
	s_mov_b32 m0, s7
	v_readfirstlane_b32 s7, v171
	global_load_lds_dwordx4 v[64:65], off
	s_mov_b32 m0, s7
	v_lshl_add_u64 v[64:65], v[90:91], 1, s[12:13]
	global_load_lds_dwordx4 v177, s[0:1]
	v_readfirstlane_b32 s0, v172
	s_mov_b32 m0, s0
	s_nop 0
	global_load_lds_dwordx4 v[64:65], off

; template <class Epi>
; __device__ __forceinline__ void gemm_tile(const bf16_t* __restrict__ A, const bf16_t* __restrict__ Bt, int K, int row0, int col0, const Epi& epi, char* smem,
;                                           bool prefetched, bool nvalid, int nrow0, int ncol0) {
;     ...
;         if (kt + 1 < nk) GLDS_STAGE(cur ^ 1, pA, pB, kt + 1);
;         const char* cb = smem + cur * 2 * TILE_B;
; #pragma unroll
;         for (int ks = 0; ks < 2; ++ks) {
;             bf16x8 a[4], b[4];
; #pragma unroll
;             for (int m = 0; m < 4; ++m) a[m] = *(const bf16x8*)(cb + offA[m][ks]);
; #pragma unroll
;             for (int n = 0; n < 4; ++n) b[n] = *(const bf16x8*)(cb + offB[n][ks]);
.LBB0_766:
	v_readfirstlane_b32 s98, v106
	v_readfirstlane_b32 s99, v107
	v_readfirstlane_b32 s10, v108
	v_readfirstlane_b32 s100, v120
	v_readfirstlane_b32 s101, v121
	v_readfirstlane_b32 s13, v149
	s_nop 3
	s_sub_u32 s16, s10, s98
	s_and_b32 s98, s98, 0xffffff80
	s_and_b32 s100, s100, 0xffffff80
	s_nop 1
	v_subrev_u32_e32 v254, s98, v106
	v_subrev_u32_e32 v255, s100, v120
	s_add_i32 s12, s13, 0x8000
	s_mov_b32 m0, s12
	s_nop 0
	global_load_lds_dwordx4 v254, s[98:99]
	s_add_i32 m0, s12, 0x1000
	s_add_u32 s10, s98, s16
	s_addc_u32 s11, s99, 0
	global_load_lds_dwordx4 v254, s[10:11]
	s_add_i32 m0, s12, 0x2000
	s_add_u32 s10, s10, s16
	s_addc_u32 s11, s11, 0
	global_load_lds_dwordx4 v254, s[10:11]
	s_add_i32 m0, s12, 0x3000
	s_add_u32 s10, s10, s16
	s_addc_u32 s11, s11, 0
	global_load_lds_dwordx4 v254, s[10:11]
	s_add_u32 s98, s98, 0x80
	s_addc_u32 s99, s99, 0
	ds_read_b128 v[190:193], v128
	ds_read_b128 v[106:109], v131 offset:16384
	ds_read_b128 v[118:121], v131 offset:16896
	ds_read_b128 v[122:125], v131 offset:20480
	ds_read_b128 v[170:173], v131 offset:20992
	ds_read_b128 v[194:197], v128 offset:2048
	ds_read_b128 v[198:201], v128 offset:4096
	ds_read_b128 v[246:249], v128 offset:6144
	s_setprio 1

; __device__ __forceinline__ f32x4 mfma16(bf16x8 a, bf16x8 b, f32x4 c) { return __builtin_amdgcn_mfma_f32_16x16x32_bf16(a, b, c, 0, 0, 0); }
; template <class Epi>
; __device__ __forceinline__ void gemm_tile(const bf16_t* __restrict__ A, const bf16_t* __restrict__ Bt, int K, int row0, int col0, const Epi& epi, char* smem,
;                                           bool prefetched, bool nvalid, int nrow0, int ncol0) {
;     ...
;     for (int kt = 0; kt < nk; ++kt) {
;         const int cur = kt & 1;
;         if (kt + 1 < nk) GLDS_STAGE(cur ^ 1, pA, pB, kt + 1);
;         const char* cb = smem + cur * 2 * TILE_B;
; #pragma unroll
;         for (int ks = 0; ks < 2; ++ks) {
;             bf16x8 a[4], b[4];
; #pragma unroll
;             for (int m = 0; m < 4; ++m) a[m] = *(const bf16x8*)(cb + offA[m][ks]);
; #pragma unroll
;             for (int n = 0; n < 4; ++n) b[n] = *(const bf16x8*)(cb + offB[n][ks]);
; #pragma unroll
;             for (int m = 0; m < 4; ++m)
; #pragma unroll
;                 for (int n = 0; n < 4; ++n) acc[m][n] = mfma16(b[n], a[m], acc[m][n]);
;         }
;         asm volatile("s_waitcnt vmcnt(0)" ::: "memory");
;         __syncthreads();
;     }
;     if (nvalid) { const bf16_t* qA = A + (size_t)nrow0 * K; const bf16_t* qB = Bt + (size_t)ncol0 * K; GLDS_STAGE(0, qA, qB, 0); }
; template <class E1, class E2>
; __device__ __forceinline__ void gemm_phase2(const bf16_t* A1, const bf16_t* B1, int M1, int N1, const E1& e1,
;                                             const bf16_t* A2, const bf16_t* B2, int M2, int N2, const E2& e2, int K, char* smem) {
;     ...
;     for (int i = (blockIdx.x + (G >> 1)) % G; i < nt2; i += G) {
;         const int j = i + G; const bool nv = j < nt2;
;         gemm_tile(A2, B2, K, (i % nM2) << 7, (i / nM2) << 7, e2, smem, pre, nv, (j % nM2) << 7, (j / nM2) << 7);
;         pre = nv;
.Lgk_tail_766:
	s_setprio 0
	v_mfma_f32_16x16x32_bf16 v[32:35], v[174:177], v[198:201], v[32:35]
	v_mfma_f32_16x16x32_bf16 v[36:39], v[178:181], v[198:201], v[36:39]
	v_mfma_f32_16x16x32_bf16 v[40:43], v[182:185], v[198:201], v[40:43]
	v_mfma_f32_16x16x32_bf16 v[44:47], v[186:189], v[198:201], v[44:47]
	v_mfma_f32_16x16x32_bf16 v[48:51], v[174:177], v[246:249], v[48:51]
	v_mfma_f32_16x16x32_bf16 v[52:55], v[178:181], v[246:249], v[52:55]
	v_mfma_f32_16x16x32_bf16 v[56:59], v[182:185], v[246:249], v[56:59]
	v_mfma_f32_16x16x32_bf16 v[60:63], v[186:189], v[246:249], v[60:63]
	ds_read_b128 v[106:109], v131 offset:49152
	ds_read_b128 v[118:121], v128 offset:32768
	ds_read_b128 v[122:125], v131 offset:49664
	ds_read_b128 v[170:173], v131 offset:53248
	ds_read_b128 v[174:177], v131 offset:53760
	v_readlane_b32 s1, v245, 59
	s_waitcnt lgkmcnt(3)
	v_mfma_f32_16x16x32_bf16 v[0:3], v[106:109], v[118:121], v[0:3]
	s_add_i32 s1, s1, s58
	s_cmpk_gt_i32 s1, 0x7ff
	s_cselect_b64 s[6:7], -1, 0
	s_waitcnt lgkmcnt(2)
	v_mfma_f32_16x16x32_bf16 v[4:7], v[122:125], v[118:121], v[4:7]
	ds_read_b128 v[190:193], v130 offset:49152
	s_cmpk_lt_i32 s1, 0x800
	v_writelane_b32 v245, s1, 59
	s_waitcnt lgkmcnt(2)
	v_mfma_f32_16x16x32_bf16 v[8:11], v[170:173], v[118:121], v[8:11]
	ds_read_b128 v[194:197], v130 offset:53248
	ds_read_b128 v[198:201], v130 offset:53760
	s_waitcnt lgkmcnt(3)
	v_mfma_f32_16x16x32_bf16 v[12:15], v[174:177], v[118:121], v[12:15]
	ds_read_b128 v[118:121], v128 offset:34816
	s_waitcnt lgkmcnt(0)
	v_mfma_f32_16x16x32_bf16 v[16:19], v[106:109], v[118:121], v[16:19]
	v_mfma_f32_16x16x32_bf16 v[20:23], v[122:125], v[118:121], v[20:23]
	v_mfma_f32_16x16x32_bf16 v[24:27], v[170:173], v[118:121], v[24:27]
	v_mfma_f32_16x16x32_bf16 v[28:31], v[174:177], v[118:121], v[28:31]
	ds_read_b128 v[118:121], v128 offset:36864
	s_waitcnt lgkmcnt(0)
	v_mfma_f32_16x16x32_bf16 v[178:181], v[106:109], v[118:121], v[32:35]
	s_nop 2
	ds_read_b128 v[32:35], v128 offset:38912
	v_mfma_f32_16x16x32_bf16 v[182:185], v[122:125], v[118:121], v[36:39]
	v_mfma_f32_16x16x32_bf16 v[186:189], v[170:173], v[118:121], v[40:43]
	v_mfma_f32_16x16x32_bf16 v[118:121], v[174:177], v[118:121], v[44:47]
	s_waitcnt lgkmcnt(0)
	v_mfma_f32_16x16x32_bf16 v[106:109], v[106:109], v[32:35], v[48:51]
	v_mfma_f32_16x16x32_bf16 v[122:125], v[122:125], v[32:35], v[52:55]
	v_mfma_f32_16x16x32_bf16 v[170:173], v[170:173], v[32:35], v[56:59]
	v_mfma_f32_16x16x32_bf16 v[174:177], v[174:177], v[32:35], v[60:63]
	ds_read_b128 v[32:35], v129 offset:32768
	s_waitcnt lgkmcnt(0)
	v_mfma_f32_16x16x32_bf16 v[56:59], v[190:193], v[32:35], v[0:3]
	s_nop 2
	ds_read_b128 v[0:3], v130 offset:49664
	s_waitcnt lgkmcnt(0)
	v_mfma_f32_16x16x32_bf16 v[60:63], v[0:3], v[32:35], v[4:7]
	s_nop 2
	ds_read_b128 v[4:7], v129 offset:34816
	v_mfma_f32_16x16x32_bf16 v[48:51], v[194:197], v[32:35], v[8:11]
	v_mfma_f32_16x16x32_bf16 v[52:55], v[198:201], v[32:35], v[12:15]
	s_nop 2
	ds_read_b128 v[12:15], v129 offset:38912
	s_waitcnt lgkmcnt(1)
	v_mfma_f32_16x16x32_bf16 v[44:47], v[190:193], v[4:7], v[16:19]
	v_mfma_f32_16x16x32_bf16 v[40:43], v[0:3], v[4:7], v[20:23]
	v_mfma_f32_16x16x32_bf16 v[36:39], v[194:197], v[4:7], v[24:27]
	v_mfma_f32_16x16x32_bf16 v[32:35], v[198:201], v[4:7], v[28:31]
	ds_read_b128 v[4:7], v129 offset:36864
	s_waitcnt vmcnt(0)
	s_waitcnt lgkmcnt(0)
	v_mfma_f32_16x16x32_bf16 v[28:31], v[190:193], v[4:7], v[178:181]
	s_barrier
	v_mfma_f32_16x16x32_bf16 v[24:27], v[0:3], v[4:7], v[182:185]
	v_mfma_f32_16x16x32_bf16 v[20:23], v[194:197], v[4:7], v[186:189]
	v_mfma_f32_16x16x32_bf16 v[16:19], v[198:201], v[4:7], v[118:121]
	v_mfma_f32_16x16x32_bf16 v[4:7], v[190:193], v[12:15], v[106:109]
	v_mfma_f32_16x16x32_bf16 v[8:11], v[0:3], v[12:15], v[122:125]
	v_mfma_f32_16x16x32_bf16 v[0:3], v[194:197], v[12:15], v[170:173]
	v_mfma_f32_16x16x32_bf16 v[12:15], v[198:201], v[12:15], v[174:177]
	s_cbranch_scc0 .LBB0_760
	v_readlane_b32 s9, v245, 59
	s_nop 0
	s_and_b32 s1, s9, 7
	s_lshl_b32 s1, s1, 3
	s_bfe_u32 s8, s9, 0x30003
	s_or_b32 s1, s1, s8
	s_and_b32 s9, s9, 0xffffffc0
	s_or_b32 s9, s9, s1
	s_ashr_i32 s1, s9, 31
	s_lshr_b32 s1, s1, 29
	s_add_i32 s1, s9, s1
	s_and_b32 s8, s1, 0x1fffff8
	s_sub_i32 s8, s9, s8
	s_lshl_b32 s8, s8, 7
	s_lshl_b32 s1, s1, 4
	s_ashr_i32 s9, s8, 31
	s_and_b32 s10, s1, 0xffffff80
	s_lshl_b64 s[8:9], s[8:9], 11
	s_add_u32 s8, s14, s8
	s_addc_u32 s9, s15, s9
	s_ashr_i32 s11, s10, 31
	s_lshl_b64 s[10:11], s[10:11], 11
	v_readlane_b32 s1, v245, 53
	s_add_u32 s10, s1, s10
	v_readlane_b32 s1, v245, 54
	s_addc_u32 s11, s1, s11
	v_readfirstlane_b32 s1, v149
	s_mov_b32 m0, s1
	v_readfirstlane_b32 s1, v132
	global_load_lds_dwordx4 v144, s[8:9]
	v_lshl_add_u64 v[106:107], v[64:65], 1, s[10:11]
	s_mov_b32 m0, s1
	v_readfirstlane_b32 s1, v133
	global_load_lds_dwordx4 v[106:107], off
	s_mov_b32 m0, s1
	v_readfirstlane_b32 s1, v134
	global_load_lds_dwordx4 v145, s[8:9]
	v_lshl_add_u64 v[106:107], v[66:67], 1, s[10:11]
	s_mov_b32 m0, s1
	v_readfirstlane_b32 s1, v135
	global_load_lds_dwordx4 v[106:107], off
	s_mov_b32 m0, s1
	v_readfirstlane_b32 s1, v136
	global_load_lds_dwordx4 v162, s[8:9]
	v_lshl_add_u64 v[106:107], v[68:69], 1, s[10:11]
	s_mov_b32 m0, s1
	v_readfirstlane_b32 s1, v137
	global_load_lds_dwordx4 v[106:107], off
	s_mov_b32 m0, s1
	v_readfirstlane_b32 s1, v141
	global_load_lds_dwordx4 v163, s[8:9]
	v_lshl_add_u64 v[106:107], v[70:71], 1, s[10:11]
	s_mov_b32 m0, s1
	s_nop 0
	global_load_lds_dwordx4 v[106:107], off
	s_branch .LBB0_760

; __device__ __forceinline__ f32x4 mfma16(bf16x8 a, bf16x8 b, f32x4 c) { return __builtin_amdgcn_mfma_f32_16x16x32_bf16(a, b, c, 0, 0, 0); }
; template <class Epi>
; __device__ __forceinline__ void gemm_tile(const bf16_t* __restrict__ A, const bf16_t* __restrict__ Bt, int K, int row0, int col0, const Epi& epi, char* smem,
;                                           bool prefetched, bool nvalid, int nrow0, int ncol0) {
;     ...
;     for (int kt = 0; kt < nk; ++kt) {
;         const int cur = kt & 1;
;         if (kt + 1 < nk) GLDS_STAGE(cur ^ 1, pA, pB, kt + 1);
;         const char* cb = smem + cur * 2 * TILE_B;
; #pragma unroll
;         for (int ks = 0; ks < 2; ++ks) {
;             bf16x8 a[4], b[4];
; #pragma unroll
;             for (int m = 0; m < 4; ++m) a[m] = *(const bf16x8*)(cb + offA[m][ks]);
; #pragma unroll
;             for (int n = 0; n < 4; ++n) b[n] = *(const bf16x8*)(cb + offB[n][ks]);
; #pragma unroll
;             for (int m = 0; m < 4; ++m)
; #pragma unroll
;                 for (int n = 0; n < 4; ++n) acc[m][n] = mfma16(b[n], a[m], acc[m][n]);
;         }
;         asm volatile("s_waitcnt vmcnt(0)" ::: "memory");
;         __syncthreads();
;     }
;     if (nvalid) { const bf16_t* qA = A + (size_t)nrow0 * K; const bf16_t* qB = Bt + (size_t)ncol0 * K; GLDS_STAGE(0, qA, qB, 0); }
; template <class Epi>
; __device__ __forceinline__ void gemm_phase(const bf16_t* A, const bf16_t* Bt, int M, int N, int K, const Epi& epi, char* smem) {
;     ...
;     for (int i = blockIdx.x; i < ntiles; i += G) {
;         const int j = i + G; const bool nv = j < ntiles;
;         gemm_tile(A, Bt, K, (i / nN) << 7, (i % nN) << 7, epi, smem, pre, nv, (j / nN) << 7, (j % nN) << 7);
;         pre = nv;
.Lgk_tail_895:
	s_setprio 0
	v_mfma_f32_16x16x32_bf16 v[32:35], v[132:135], v[246:249], v[32:35]
	v_mfma_f32_16x16x32_bf16 v[36:39], v[136:139], v[246:249], v[36:39]
	v_mfma_f32_16x16x32_bf16 v[40:43], v[140:143], v[246:249], v[40:43]
	v_mfma_f32_16x16x32_bf16 v[44:47], v[170:173], v[246:249], v[44:47]
	v_mfma_f32_16x16x32_bf16 v[48:51], v[132:135], v[250:253], v[48:51]
	v_mfma_f32_16x16x32_bf16 v[52:55], v[136:139], v[250:253], v[52:55]
	v_mfma_f32_16x16x32_bf16 v[56:59], v[140:143], v[250:253], v[56:59]
	v_mfma_f32_16x16x32_bf16 v[60:63], v[170:173], v[250:253], v[60:63]
	ds_read_b128 v[92:95], v110 offset:49152
	ds_read_b128 v[96:99], v110 offset:49664
	ds_read_b128 v[100:103], v108 offset:32768
	ds_read_b128 v[104:107], v108 offset:34816
	ds_read_b128 v[132:135], v110 offset:53248
	ds_read_b128 v[136:139], v110 offset:53760
	s_add_i32 s16, s16, s58
	s_waitcnt lgkmcnt(3)
	v_mfma_f32_16x16x32_bf16 v[0:3], v[92:95], v[100:103], v[0:3]
	s_cmpk_gt_i32 s16, 0x7ff
	s_cselect_b64 s[6:7], -1, 0
	s_cmpk_lt_i32 s16, 0x800
	v_mfma_f32_16x16x32_bf16 v[4:7], v[96:99], v[100:103], v[4:7]
	s_waitcnt lgkmcnt(1)
	v_mfma_f32_16x16x32_bf16 v[8:11], v[132:135], v[100:103], v[8:11]
	s_waitcnt lgkmcnt(0)
	v_mfma_f32_16x16x32_bf16 v[12:15], v[136:139], v[100:103], v[12:15]
	v_mfma_f32_16x16x32_bf16 v[16:19], v[92:95], v[104:107], v[16:19]
	v_mfma_f32_16x16x32_bf16 v[20:23], v[96:99], v[104:107], v[20:23]
	v_mfma_f32_16x16x32_bf16 v[24:27], v[132:135], v[104:107], v[24:27]
	v_mfma_f32_16x16x32_bf16 v[28:31], v[136:139], v[104:107], v[28:31]
	ds_read_b128 v[100:103], v108 offset:36864
	ds_read_b128 v[104:107], v108 offset:38912
	ds_read_b128 v[178:181], v111 offset:49152
	s_waitcnt lgkmcnt(2)
	v_mfma_f32_16x16x32_bf16 v[140:143], v[92:95], v[100:103], v[32:35]
	v_mfma_f32_16x16x32_bf16 v[170:173], v[96:99], v[100:103], v[36:39]
	v_mfma_f32_16x16x32_bf16 v[174:177], v[132:135], v[100:103], v[40:43]
	v_mfma_f32_16x16x32_bf16 v[100:103], v[136:139], v[100:103], v[44:47]
	s_waitcnt lgkmcnt(1)
	v_mfma_f32_16x16x32_bf16 v[92:95], v[92:95], v[104:107], v[48:51]
	v_mfma_f32_16x16x32_bf16 v[96:99], v[96:99], v[104:107], v[52:55]
	v_mfma_f32_16x16x32_bf16 v[132:135], v[132:135], v[104:107], v[56:59]
	v_mfma_f32_16x16x32_bf16 v[104:107], v[136:139], v[104:107], v[60:63]
	ds_read_b128 v[136:139], v111 offset:49664
	ds_read_b128 v[32:35], v109 offset:32768
	ds_read_b128 v[36:39], v109 offset:34816
	ds_read_b128 v[182:185], v111 offset:53760
	s_waitcnt lgkmcnt(2)
	v_mfma_f32_16x16x32_bf16 v[52:55], v[178:181], v[32:35], v[0:3]
	s_nop 2
	ds_read_b128 v[0:3], v111 offset:53248
	v_mfma_f32_16x16x32_bf16 v[56:59], v[136:139], v[32:35], v[4:7]
	s_nop 2
	ds_read_b128 v[4:7], v109 offset:36864
	ds_read_b128 v[186:189], v109 offset:38912
	s_waitcnt vmcnt(0)
	s_waitcnt lgkmcnt(0)
	v_mfma_f32_16x16x32_bf16 v[60:63], v[0:3], v[32:35], v[8:11]
	s_barrier
	v_mfma_f32_16x16x32_bf16 v[48:51], v[182:185], v[32:35], v[12:15]
	v_mfma_f32_16x16x32_bf16 v[44:47], v[178:181], v[36:39], v[16:19]
	v_mfma_f32_16x16x32_bf16 v[40:43], v[136:139], v[36:39], v[20:23]
	v_mfma_f32_16x16x32_bf16 v[32:35], v[0:3], v[36:39], v[24:27]
	v_mfma_f32_16x16x32_bf16 v[24:27], v[182:185], v[36:39], v[28:31]
	v_mfma_f32_16x16x32_bf16 v[36:39], v[178:181], v[4:7], v[140:143]
	v_mfma_f32_16x16x32_bf16 v[28:31], v[136:139], v[4:7], v[170:173]
	v_mfma_f32_16x16x32_bf16 v[20:23], v[0:3], v[4:7], v[174:177]
	v_mfma_f32_16x16x32_bf16 v[16:19], v[182:185], v[4:7], v[100:103]
	v_mfma_f32_16x16x32_bf16 v[12:15], v[178:181], v[186:189], v[92:95]
	v_mfma_f32_16x16x32_bf16 v[8:11], v[136:139], v[186:189], v[96:99]
	v_mfma_f32_16x16x32_bf16 v[4:7], v[0:3], v[186:189], v[132:135]
	v_mfma_f32_16x16x32_bf16 v[0:3], v[182:185], v[186:189], v[104:107]
	s_cbranch_scc0 .LBB0_889
	s_and_b32 s12, s16, 7
	s_lshl_b32 s12, s12, 3
	s_bfe_u32 s13, s16, 0x30003
	s_or_b32 s12, s12, s13
	s_and_b32 s13, s16, 0xffffffc0
	s_or_b32 s13, s12, s13
	s_ashr_i32 s1, s13, 31
	s_lshr_b32 s1, s1, 29
	s_add_i32 s1, s13, s1
	s_lshl_b32 s3, s1, 4
	s_and_b32 s8, s3, 0xffffff80
	s_and_b32 s1, s1, 0x1fffff8
	s_sub_i32 s1, s13, s1
	s_ashr_i32 s9, s8, 31
	s_lshl_b32 s10, s1, 7
	s_lshl_b64 s[8:9], s[8:9], 11
	v_readlane_b32 s12, v245, 60
	v_readlane_b32 s13, v245, 61
	s_add_u32 s8, s12, s8
	s_addc_u32 s9, s13, s9
	s_ashr_i32 s11, s10, 31
	s_lshl_b64 s[10:11], s[10:11], 11
	s_add_u32 s10, s14, s10
	v_readfirstlane_b32 s1, v149
	s_addc_u32 s11, s15, s11
	s_mov_b32 m0, s1
	v_readfirstlane_b32 s1, v118
	global_load_lds_dwordx4 v125, s[8:9]
	v_lshl_add_u64 v[92:93], v[64:65], 1, s[10:11]
	s_mov_b32 m0, s1
	v_readfirstlane_b32 s1, v119
	global_load_lds_dwordx4 v[92:93], off
	s_mov_b32 m0, s1
	v_readfirstlane_b32 s1, v120
	global_load_lds_dwordx4 v126, s[8:9]
	v_lshl_add_u64 v[92:93], v[66:67], 1, s[10:11]
	s_mov_b32 m0, s1
	v_readfirstlane_b32 s1, v121
	global_load_lds_dwordx4 v[92:93], off
	s_mov_b32 m0, s1
	v_readfirstlane_b32 s1, v122
	global_load_lds_dwordx4 v127, s[8:9]
	v_lshl_add_u64 v[92:93], v[68:69], 1, s[10:11]
	s_mov_b32 m0, s1
	v_readfirstlane_b32 s1, v123
	global_load_lds_dwordx4 v[92:93], off
	s_mov_b32 m0, s1
	v_readfirstlane_b32 s1, v124
	global_load_lds_dwordx4 v130, s[8:9]
	v_lshl_add_u64 v[92:93], v[70:71], 1, s[10:11]
	s_mov_b32 m0, s1
	s_nop 0
	global_load_lds_dwordx4 v[92:93], off
	s_branch .LBB0_889

; template <class Epi>
; __device__ __forceinline__ void gemm_tile(const bf16_t* __restrict__ A, const bf16_t* __restrict__ Bt, int K, int row0, int col0, const Epi& epi, char* smem,
;                                           bool prefetched, bool nvalid, int nrow0, int ncol0) {
;     ...
;         if (kt + 1 < nk) GLDS_STAGE(cur ^ 1, pA, pB, kt + 1);
;         const char* cb = smem + cur * 2 * TILE_B;
; #pragma unroll
;         for (int ks = 0; ks < 2; ++ks) {
;             bf16x8 a[4], b[4];
; #pragma unroll
;             for (int m = 0; m < 4; ++m) a[m] = *(const bf16x8*)(cb + offA[m][ks]);
; #pragma unroll
;             for (int n = 0; n < 4; ++n) b[n] = *(const bf16x8*)(cb + offB[n][ks]);
.LBB0_998:
	v_readfirstlane_b32 s98, v106
	v_readfirstlane_b32 s99, v107
	v_readfirstlane_b32 s10, v108
	v_readfirstlane_b32 s100, v120
	v_readfirstlane_b32 s101, v121
	v_readfirstlane_b32 s17, v149
	s_nop 3
	s_sub_u32 s18, s10, s98
	s_and_b32 s98, s98, 0xffffff80
	s_and_b32 s100, s100, 0xffffff80
	s_nop 1
	v_subrev_u32_e32 v254, s98, v106
	v_subrev_u32_e32 v255, s100, v120
	s_add_i32 s13, s17, 0x8000
	s_mov_b32 m0, s13
	s_nop 0
	global_load_lds_dwordx4 v254, s[98:99]
	s_add_i32 m0, s13, 0x1000
	s_add_u32 s10, s98, s18
	s_addc_u32 s11, s99, 0
	global_load_lds_dwordx4 v254, s[10:11]
	s_add_i32 m0, s13, 0x2000
	s_add_u32 s10, s10, s18
	s_addc_u32 s11, s11, 0
	global_load_lds_dwordx4 v254, s[10:11]
	s_add_i32 m0, s13, 0x3000
	s_add_u32 s10, s10, s18
	s_addc_u32 s11, s11, 0
	global_load_lds_dwordx4 v254, s[10:11]
	s_add_u32 s98, s98, 0x80
	s_addc_u32 s99, s99, 0
	ds_read_b128 v[184:187], v130
	ds_read_b128 v[106:109], v133 offset:16384
	ds_read_b128 v[118:121], v133 offset:16896
	ds_read_b128 v[122:125], v133 offset:20480
	ds_read_b128 v[158:161], v133 offset:20992
	ds_read_b128 v[188:191], v130 offset:2048
	ds_read_b128 v[246:249], v130 offset:4096
	ds_read_b128 v[250:253], v130 offset:6144
	s_setprio 1

; __device__ __forceinline__ f32x4 mfma16(bf16x8 a, bf16x8 b, f32x4 c) { return __builtin_amdgcn_mfma_f32_16x16x32_bf16(a, b, c, 0, 0, 0); }
; template <class Epi>
; __device__ __forceinline__ void gemm_tile(const bf16_t* __restrict__ A, const bf16_t* __restrict__ Bt, int K, int row0, int col0, const Epi& epi, char* smem,
;                                           bool prefetched, bool nvalid, int nrow0, int ncol0) {
;     ...
;     for (int kt = 0; kt < nk; ++kt) {
;         const int cur = kt & 1;
;         if (kt + 1 < nk) GLDS_STAGE(cur ^ 1, pA, pB, kt + 1);
;         const char* cb = smem + cur * 2 * TILE_B;
; #pragma unroll
;         for (int ks = 0; ks < 2; ++ks) {
;             bf16x8 a[4], b[4];
; #pragma unroll
;             for (int m = 0; m < 4; ++m) a[m] = *(const bf16x8*)(cb + offA[m][ks]);
; #pragma unroll
;             for (int n = 0; n < 4; ++n) b[n] = *(const bf16x8*)(cb + offB[n][ks]);
; #pragma unroll
;             for (int m = 0; m < 4; ++m)
; #pragma unroll
;                 for (int n = 0; n < 4; ++n) acc[m][n] = mfma16(b[n], a[m], acc[m][n]);
;         }
;         asm volatile("s_waitcnt vmcnt(0)" ::: "memory");
;         __syncthreads();
;     }
;     if (nvalid) { const bf16_t* qA = A + (size_t)nrow0 * K; const bf16_t* qB = Bt + (size_t)ncol0 * K; GLDS_STAGE(0, qA, qB, 0); }
; template <class Epi>
; __device__ __forceinline__ void gemm_phase(const bf16_t* A, const bf16_t* Bt, int M, int N, int K, const Epi& epi, char* smem) {
;     ...
;     for (int i = blockIdx.x; i < ntiles; i += G) {
;         const int j = i + G; const bool nv = j < ntiles;
;         gemm_tile(A, Bt, K, (i / nN) << 7, (i % nN) << 7, epi, smem, pre, nv, (j / nN) << 7, (j % nN) << 7);
;         pre = nv;
.Lgk_tail_998:
	s_setprio 0
	v_mfma_f32_16x16x32_bf16 v[32:35], v[168:171], v[246:249], v[32:35]
	v_mfma_f32_16x16x32_bf16 v[36:39], v[172:175], v[246:249], v[36:39]
	v_mfma_f32_16x16x32_bf16 v[40:43], v[176:179], v[246:249], v[40:43]
	v_mfma_f32_16x16x32_bf16 v[44:47], v[180:183], v[246:249], v[44:47]
	v_mfma_f32_16x16x32_bf16 v[48:51], v[168:171], v[250:253], v[48:51]
	v_mfma_f32_16x16x32_bf16 v[52:55], v[172:175], v[250:253], v[52:55]
	v_mfma_f32_16x16x32_bf16 v[56:59], v[176:179], v[250:253], v[56:59]
	v_mfma_f32_16x16x32_bf16 v[60:63], v[180:183], v[250:253], v[60:63]
	ds_read_b128 v[106:109], v133 offset:49152
	ds_read_b128 v[118:121], v130 offset:32768
	ds_read_b128 v[122:125], v133 offset:49664
	ds_read_b128 v[158:161], v133 offset:53248
	ds_read_b128 v[168:171], v133 offset:53760
	s_add_i32 s16, s16, s58
	s_waitcnt lgkmcnt(3)
	v_mfma_f32_16x16x32_bf16 v[0:3], v[106:109], v[118:121], v[0:3]
	s_cmpk_gt_i32 s16, 0x1fff
	s_cselect_b64 s[6:7], -1, 0
	s_cmpk_lt_i32 s16, 0x2000
	s_waitcnt lgkmcnt(2)
	v_mfma_f32_16x16x32_bf16 v[4:7], v[122:125], v[118:121], v[4:7]
	ds_read_b128 v[184:187], v132 offset:49152
	ds_read_b128 v[188:191], v132 offset:53760
	s_waitcnt lgkmcnt(3)
	v_mfma_f32_16x16x32_bf16 v[8:11], v[158:161], v[118:121], v[8:11]
	s_waitcnt lgkmcnt(2)
	v_mfma_f32_16x16x32_bf16 v[12:15], v[168:171], v[118:121], v[12:15]
	ds_read_b128 v[118:121], v130 offset:34816
	s_waitcnt lgkmcnt(0)
	v_mfma_f32_16x16x32_bf16 v[16:19], v[106:109], v[118:121], v[16:19]
	v_mfma_f32_16x16x32_bf16 v[20:23], v[122:125], v[118:121], v[20:23]
	v_mfma_f32_16x16x32_bf16 v[24:27], v[158:161], v[118:121], v[24:27]
	v_mfma_f32_16x16x32_bf16 v[28:31], v[168:171], v[118:121], v[28:31]
	ds_read_b128 v[118:121], v130 offset:36864
	s_waitcnt lgkmcnt(0)
	v_mfma_f32_16x16x32_bf16 v[172:175], v[106:109], v[118:121], v[32:35]
	s_nop 2
	ds_read_b128 v[32:35], v130 offset:38912
	v_mfma_f32_16x16x32_bf16 v[176:179], v[122:125], v[118:121], v[36:39]
	v_mfma_f32_16x16x32_bf16 v[180:183], v[158:161], v[118:121], v[40:43]
	v_mfma_f32_16x16x32_bf16 v[118:121], v[168:171], v[118:121], v[44:47]
	s_waitcnt lgkmcnt(0)
	v_mfma_f32_16x16x32_bf16 v[106:109], v[106:109], v[32:35], v[48:51]
	v_mfma_f32_16x16x32_bf16 v[122:125], v[122:125], v[32:35], v[52:55]
	v_mfma_f32_16x16x32_bf16 v[158:161], v[158:161], v[32:35], v[56:59]
	v_mfma_f32_16x16x32_bf16 v[168:171], v[168:171], v[32:35], v[60:63]
	ds_read_b128 v[32:35], v131 offset:32768
	s_waitcnt lgkmcnt(0)
	v_mfma_f32_16x16x32_bf16 v[56:59], v[184:187], v[32:35], v[0:3]
	s_nop 2
	ds_read_b128 v[0:3], v132 offset:49664
	s_waitcnt lgkmcnt(0)
	v_mfma_f32_16x16x32_bf16 v[60:63], v[0:3], v[32:35], v[4:7]
	s_nop 2
	ds_read_b128 v[4:7], v132 offset:53248
	s_waitcnt lgkmcnt(0)
	v_mfma_f32_16x16x32_bf16 v[48:51], v[4:7], v[32:35], v[8:11]
	s_nop 2
	ds_read_b128 v[8:11], v131 offset:34816
	v_mfma_f32_16x16x32_bf16 v[52:55], v[188:191], v[32:35], v[12:15]
	s_waitcnt lgkmcnt(0)
	v_mfma_f32_16x16x32_bf16 v[44:47], v[184:187], v[8:11], v[16:19]
	v_mfma_f32_16x16x32_bf16 v[40:43], v[0:3], v[8:11], v[20:23]
	v_mfma_f32_16x16x32_bf16 v[36:39], v[4:7], v[8:11], v[24:27]
	v_mfma_f32_16x16x32_bf16 v[32:35], v[188:191], v[8:11], v[28:31]
	ds_read_b128 v[8:11], v131 offset:36864
	s_waitcnt lgkmcnt(0)
	v_mfma_f32_16x16x32_bf16 v[16:19], v[188:191], v[8:11], v[118:121]
	s_nop 2
	ds_read_b128 v[118:121], v131 offset:38912
	s_waitcnt vmcnt(0)
	v_mfma_f32_16x16x32_bf16 v[28:31], v[184:187], v[8:11], v[172:175]
	s_waitcnt lgkmcnt(0)
	s_barrier
	v_mfma_f32_16x16x32_bf16 v[24:27], v[0:3], v[8:11], v[176:179]
	v_mfma_f32_16x16x32_bf16 v[20:23], v[4:7], v[8:11], v[180:183]
	v_mfma_f32_16x16x32_bf16 v[8:11], v[184:187], v[118:121], v[106:109]
	v_mfma_f32_16x16x32_bf16 v[12:15], v[0:3], v[118:121], v[122:125]
	v_mfma_f32_16x16x32_bf16 v[0:3], v[4:7], v[118:121], v[158:161]
	v_mfma_f32_16x16x32_bf16 v[4:7], v[188:191], v[118:121], v[168:171]
	s_cbranch_scc0 .LBB0_992
	s_and_b32 s10, s16, 7
	s_lshl_b32 s10, s10, 3
	s_bfe_u32 s11, s16, 0x30006
	s_or_b32 s10, s10, s11
	s_lshr_b32 s11, s16, 11
	s_lshl_b32 s11, s11, 6
	s_or_b32 s10, s10, s11
	s_lshl_b32 s10, s10, 5
	s_bfe_u32 s11, s16, 0x30003
	s_or_b32 s10, s10, s11
	s_bfe_u32 s11, s16, 0x20009
	s_lshl_b32 s11, s11, 3
	s_or_b32 s11, s10, s11
	s_ashr_i32 s8, s11, 31
	s_lshr_b32 s8, s8, 27
	s_add_i32 s9, s11, s8
	s_lshl_b32 s8, s9, 2
	s_and_b32 s9, s9, 0x1ffffe0
	s_and_b32 s8, s8, 0xffffff80
	s_sub_i32 s9, s11, s9
	s_lshl_b32 s10, s9, 7
	s_ashr_i32 s9, s8, 31
	s_lshl_b64 s[8:9], s[8:9], 11
	v_readlane_b32 s11, v245, 53
	s_add_u32 s8, s11, s8
	v_readlane_b32 s11, v245, 54
	s_addc_u32 s9, s11, s9
	s_ashr_i32 s11, s10, 31
	s_lshl_b64 s[10:11], s[10:11], 11
	s_add_u32 s10, s14, s10
	v_readfirstlane_b32 s12, v149
	s_addc_u32 s11, s15, s11
	s_mov_b32 m0, s12
	v_readfirstlane_b32 s12, v134
	global_load_lds_dwordx4 v143, s[8:9]
	v_lshl_add_u64 v[106:107], v[64:65], 1, s[10:11]
	s_mov_b32 m0, s12
	v_readfirstlane_b32 s12, v135
	global_load_lds_dwordx4 v[106:107], off
	s_mov_b32 m0, s12
	v_readfirstlane_b32 s12, v136
	global_load_lds_dwordx4 v144, s[8:9]
	v_lshl_add_u64 v[106:107], v[66:67], 1, s[10:11]
	s_mov_b32 m0, s12
	v_readfirstlane_b32 s12, v137
	global_load_lds_dwordx4 v[106:107], off
	s_mov_b32 m0, s12
	v_readfirstlane_b32 s12, v138
	global_load_lds_dwordx4 v145, s[8:9]
	v_lshl_add_u64 v[106:107], v[68:69], 1, s[10:11]
	s_mov_b32 m0, s12
	v_readfirstlane_b32 s12, v139
	global_load_lds_dwordx4 v[106:107], off
	s_mov_b32 m0, s12
	v_lshl_add_u64 v[106:107], v[70:71], 1, s[10:11]
	global_load_lds_dwordx4 v157, s[8:9]
	v_readfirstlane_b32 s8, v140
	s_mov_b32 m0, s8
	s_nop 0
	global_load_lds_dwordx4 v[106:107], off
	s_branch .LBB0_992

; template <class Epi>
; __device__ __forceinline__ void gemm_tile(const bf16_t* __restrict__ A, const bf16_t* __restrict__ Bt, int K, int row0, int col0, const Epi& epi, char* smem,
;                                           bool prefetched, bool nvalid, int nrow0, int ncol0) {
;     ...
;         if (kt + 1 < nk) GLDS_STAGE(cur ^ 1, pA, pB, kt + 1);
;         const char* cb = smem + cur * 2 * TILE_B;
; #pragma unroll
;         for (int ks = 0; ks < 2; ++ks) {
;             bf16x8 a[4], b[4];
; #pragma unroll
;             for (int m = 0; m < 4; ++m) a[m] = *(const bf16x8*)(cb + offA[m][ks]);
; #pragma unroll
;             for (int n = 0; n < 4; ++n) b[n] = *(const bf16x8*)(cb + offB[n][ks]);
.LBB0_1054:
	v_readfirstlane_b32 s98, v92
	v_readfirstlane_b32 s99, v93
	v_readfirstlane_b32 s6, v94
	v_readfirstlane_b32 s100, v100
	v_readfirstlane_b32 s101, v101
	v_readfirstlane_b32 s10, v149
	s_nop 3
	s_sub_u32 s11, s6, s98
	s_and_b32 s98, s98, 0xffffff80
	s_and_b32 s100, s100, 0xffffff80
	s_nop 1
	v_subrev_u32_e32 v254, s98, v92
	v_subrev_u32_e32 v255, s100, v100
	s_add_i32 s9, s10, 0x8000
	s_mov_b32 m0, s9
	s_nop 0
	global_load_lds_dwordx4 v254, s[98:99]
	s_add_i32 m0, s9, 0x1000
	s_add_u32 s6, s98, s11
	s_addc_u32 s7, s99, 0
	global_load_lds_dwordx4 v254, s[6:7]
	s_add_i32 m0, s9, 0x2000
	s_add_u32 s6, s6, s11
	s_addc_u32 s7, s7, 0
	global_load_lds_dwordx4 v254, s[6:7]
	s_add_i32 m0, s9, 0x3000
	s_add_u32 s6, s6, s11
	s_addc_u32 s7, s7, 0
	global_load_lds_dwordx4 v254, s[6:7]
	s_add_u32 s98, s98, 0x80
	s_addc_u32 s99, s99, 0
	ds_read_b128 v[150:153], v108
	ds_read_b128 v[92:95], v110 offset:16384
	ds_read_b128 v[96:99], v110 offset:16896
	ds_read_b128 v[100:103], v110 offset:20480
	ds_read_b128 v[104:107], v110 offset:20992
	ds_read_b128 v[154:157], v108 offset:2048
	ds_read_b128 v[246:249], v108 offset:4096
	ds_read_b128 v[250:253], v108 offset:6144
	s_setprio 1

; __device__ __forceinline__ f32x4 mfma16(bf16x8 a, bf16x8 b, f32x4 c) { return __builtin_amdgcn_mfma_f32_16x16x32_bf16(a, b, c, 0, 0, 0); }
; template <class Epi>
; __device__ __forceinline__ void gemm_tile(const bf16_t* __restrict__ A, const bf16_t* __restrict__ Bt, int K, int row0, int col0, const Epi& epi, char* smem,
;                                           bool prefetched, bool nvalid, int nrow0, int ncol0) {
;     ...
;     for (int kt = 0; kt < nk; ++kt) {
;         const int cur = kt & 1;
;         if (kt + 1 < nk) GLDS_STAGE(cur ^ 1, pA, pB, kt + 1);
;         const char* cb = smem + cur * 2 * TILE_B;
; #pragma unroll
;         for (int ks = 0; ks < 2; ++ks) {
;             bf16x8 a[4], b[4];
; #pragma unroll
;             for (int m = 0; m < 4; ++m) a[m] = *(const bf16x8*)(cb + offA[m][ks]);
; #pragma unroll
;             for (int n = 0; n < 4; ++n) b[n] = *(const bf16x8*)(cb + offB[n][ks]);
; #pragma unroll
;             for (int m = 0; m < 4; ++m)
; #pragma unroll
;                 for (int n = 0; n < 4; ++n) acc[m][n] = mfma16(b[n], a[m], acc[m][n]);
;         }
;         asm volatile("s_waitcnt vmcnt(0)" ::: "memory");
;         __syncthreads();
;     }
;     if (nvalid) { const bf16_t* qA = A + (size_t)nrow0 * K; const bf16_t* qB = Bt + (size_t)ncol0 * K; GLDS_STAGE(0, qA, qB, 0); }
; template <class Epi>
; __device__ __forceinline__ void gemm_phase(const bf16_t* A, const bf16_t* Bt, int M, int N, int K, const Epi& epi, char* smem) {
;     ...
;     for (int i = blockIdx.x; i < ntiles; i += G) {
;         const int j = i + G; const bool nv = j < ntiles;
;         gemm_tile(A, Bt, K, (i / nN) << 7, (i % nN) << 7, epi, smem, pre, nv, (j / nN) << 7, (j % nN) << 7);
;         pre = nv;
.Lgk_tail_1054:
	s_setprio 0
	v_mfma_f32_16x16x32_bf16 v[32:35], v[128:131], v[246:249], v[32:35]
	v_mfma_f32_16x16x32_bf16 v[36:39], v[132:135], v[246:249], v[36:39]
	v_mfma_f32_16x16x32_bf16 v[40:43], v[136:139], v[246:249], v[40:43]
	v_mfma_f32_16x16x32_bf16 v[44:47], v[140:143], v[246:249], v[44:47]
	v_mfma_f32_16x16x32_bf16 v[48:51], v[128:131], v[250:253], v[48:51]
	v_mfma_f32_16x16x32_bf16 v[52:55], v[132:135], v[250:253], v[52:55]
	v_mfma_f32_16x16x32_bf16 v[56:59], v[136:139], v[250:253], v[56:59]
	v_mfma_f32_16x16x32_bf16 v[60:63], v[140:143], v[250:253], v[60:63]
	ds_read_b128 v[92:95], v110 offset:49152
	ds_read_b128 v[96:99], v110 offset:49664
	ds_read_b128 v[100:103], v108 offset:32768
	ds_read_b128 v[104:107], v108 offset:34816
	ds_read_b128 v[128:131], v110 offset:53248
	ds_read_b128 v[132:135], v110 offset:53760
	s_add_i32 s16, s16, s58
	s_waitcnt lgkmcnt(3)
	v_mfma_f32_16x16x32_bf16 v[0:3], v[92:95], v[100:103], v[0:3]
	s_cmpk_gt_i32 s16, 0x7ff
	s_cselect_b64 s[4:5], -1, 0
	s_cmpk_lt_i32 s16, 0x800
	v_mfma_f32_16x16x32_bf16 v[4:7], v[96:99], v[100:103], v[4:7]
	s_waitcnt lgkmcnt(1)
	v_mfma_f32_16x16x32_bf16 v[8:11], v[128:131], v[100:103], v[8:11]
	s_waitcnt lgkmcnt(0)
	v_mfma_f32_16x16x32_bf16 v[12:15], v[132:135], v[100:103], v[12:15]
	v_mfma_f32_16x16x32_bf16 v[16:19], v[92:95], v[104:107], v[16:19]
	v_mfma_f32_16x16x32_bf16 v[20:23], v[96:99], v[104:107], v[20:23]
	v_mfma_f32_16x16x32_bf16 v[24:27], v[128:131], v[104:107], v[24:27]
	v_mfma_f32_16x16x32_bf16 v[28:31], v[132:135], v[104:107], v[28:31]
	ds_read_b128 v[100:103], v108 offset:36864
	ds_read_b128 v[104:107], v108 offset:38912
	ds_read_b128 v[154:157], v111 offset:49152
	s_waitcnt lgkmcnt(2)
	v_mfma_f32_16x16x32_bf16 v[136:139], v[92:95], v[100:103], v[32:35]
	v_mfma_f32_16x16x32_bf16 v[140:143], v[96:99], v[100:103], v[36:39]
	v_mfma_f32_16x16x32_bf16 v[150:153], v[128:131], v[100:103], v[40:43]
	v_mfma_f32_16x16x32_bf16 v[100:103], v[132:135], v[100:103], v[44:47]
	s_waitcnt lgkmcnt(1)
	v_mfma_f32_16x16x32_bf16 v[92:95], v[92:95], v[104:107], v[48:51]
	v_mfma_f32_16x16x32_bf16 v[96:99], v[96:99], v[104:107], v[52:55]
	v_mfma_f32_16x16x32_bf16 v[128:131], v[128:131], v[104:107], v[56:59]
	v_mfma_f32_16x16x32_bf16 v[104:107], v[132:135], v[104:107], v[60:63]
	ds_read_b128 v[132:135], v111 offset:49664
	ds_read_b128 v[32:35], v109 offset:32768
	ds_read_b128 v[36:39], v109 offset:34816
	ds_read_b128 v[158:161], v111 offset:53760
	s_waitcnt lgkmcnt(2)
	v_mfma_f32_16x16x32_bf16 v[52:55], v[154:157], v[32:35], v[0:3]
	s_nop 2
	ds_read_b128 v[0:3], v111 offset:53248
	v_mfma_f32_16x16x32_bf16 v[56:59], v[132:135], v[32:35], v[4:7]
	s_nop 2
	ds_read_b128 v[4:7], v109 offset:36864
	ds_read_b128 v[168:171], v109 offset:38912
	s_waitcnt vmcnt(0)
	s_waitcnt lgkmcnt(0)
	v_mfma_f32_16x16x32_bf16 v[60:63], v[0:3], v[32:35], v[8:11]
	s_barrier
	v_mfma_f32_16x16x32_bf16 v[48:51], v[158:161], v[32:35], v[12:15]
	v_mfma_f32_16x16x32_bf16 v[44:47], v[154:157], v[36:39], v[16:19]
	v_mfma_f32_16x16x32_bf16 v[40:43], v[132:135], v[36:39], v[20:23]
	v_mfma_f32_16x16x32_bf16 v[32:35], v[0:3], v[36:39], v[24:27]
	v_mfma_f32_16x16x32_bf16 v[24:27], v[158:161], v[36:39], v[28:31]
	v_mfma_f32_16x16x32_bf16 v[36:39], v[154:157], v[4:7], v[136:139]
	v_mfma_f32_16x16x32_bf16 v[28:31], v[132:135], v[4:7], v[140:143]
	v_mfma_f32_16x16x32_bf16 v[20:23], v[0:3], v[4:7], v[150:153]
	v_mfma_f32_16x16x32_bf16 v[16:19], v[158:161], v[4:7], v[100:103]
	v_mfma_f32_16x16x32_bf16 v[12:15], v[154:157], v[168:171], v[92:95]
	v_mfma_f32_16x16x32_bf16 v[8:11], v[132:135], v[168:171], v[96:99]
	v_mfma_f32_16x16x32_bf16 v[4:7], v[0:3], v[168:171], v[128:131]
	v_mfma_f32_16x16x32_bf16 v[0:3], v[158:161], v[168:171], v[104:107]
	s_cbranch_scc0 .LBB0_1048
	s_and_b32 s10, s16, 7
	s_lshl_b32 s10, s10, 3
	s_bfe_u32 s11, s16, 0x30003
	s_or_b32 s10, s10, s11
	s_and_b32 s11, s16, 0xffffffc0
	s_or_b32 s11, s10, s11
	s_ashr_i32 s1, s11, 31
	s_lshr_b32 s1, s1, 29
	s_add_i32 s1, s11, s1
	s_lshl_b32 s3, s1, 4
	s_and_b32 s6, s3, 0xffffff80
	s_and_b32 s1, s1, 0x1fffff8
	s_sub_i32 s1, s11, s1
	s_ashr_i32 s7, s6, 31
	s_lshl_b32 s8, s1, 7
	s_lshl_b64 s[6:7], s[6:7], 13
	v_readlane_b32 s10, v245, 55
	v_readlane_b32 s11, v245, 56
	s_add_u32 s6, s10, s6
	s_addc_u32 s7, s11, s7
	s_ashr_i32 s9, s8, 31
	s_lshl_b64 s[8:9], s[8:9], 13
	s_add_u32 s8, s12, s8
	v_readfirstlane_b32 s1, v149
	s_addc_u32 s9, s13, s9
	s_mov_b32 m0, s1
	v_readfirstlane_b32 s1, v114
	global_load_lds_dwordx4 v123, s[6:7]
	v_lshl_add_u64 v[92:93], v[64:65], 1, s[8:9]
	s_mov_b32 m0, s1
	v_readfirstlane_b32 s1, v116
	global_load_lds_dwordx4 v[92:93], off
	s_mov_b32 m0, s1
	v_readfirstlane_b32 s1, v118
	global_load_lds_dwordx4 v124, s[6:7]
	v_lshl_add_u64 v[92:93], v[66:67], 1, s[8:9]
	s_mov_b32 m0, s1
	v_readfirstlane_b32 s1, v119
	global_load_lds_dwordx4 v[92:93], off
	s_mov_b32 m0, s1
	v_readfirstlane_b32 s1, v120
	global_load_lds_dwordx4 v125, s[6:7]
	v_lshl_add_u64 v[92:93], v[68:69], 1, s[8:9]
	s_mov_b32 m0, s1
	v_readfirstlane_b32 s1, v121
	global_load_lds_dwordx4 v[92:93], off
	s_mov_b32 m0, s1
	v_readfirstlane_b32 s1, v122
	global_load_lds_dwordx4 v126, s[6:7]
	v_lshl_add_u64 v[92:93], v[70:71], 1, s[8:9]
	s_mov_b32 m0, s1
	s_nop 0
	global_load_lds_dwordx4 v[92:93], off
	s_branch .LBB0_1048
